# up-projection GEMM: leftover tiles of the last round as quarter units (row half x column half, 8-byte stores of the own column half) when 4x fit the grid, half units otherwise
# speedup vs baseline: 1.0086x; 1.0086x over previous
;     __host__ __device__ bool next(int i, Unit& u) const {
;         const long L = (long)i * G + c; if (L >= nwg) return false;
;         int wgid = (int)L; { const int q = nwg / NXCD, r = nwg % NXCD, xcd = wgid % NXCD, off = wgid / NXCD; wgid = (xcd < r ? xcd * (q + 1) : r * (q + 1) + (xcd - r) * q) + off; }
;         const int nig = WGM * nN, gid = wgid / nig, fm = gid * WGM, gsz = (nM - fm) < WGM ? (nM - fm) : WGM;
;         u.pm = fm + ((wgid % nig) % gsz); u.pn = (wgid % nig) / gsz; return true;
;     }
.LBB0_160:
	s_lshr_b32 s101, s101, 4
	s_add_i32 s86, s86, 1
	s_mul_i32 s6, s86, s39
	s_mul_hi_u32 s7, s86, s38
	s_add_i32 s7, s7, s6
	s_mul_i32 s6, s86, s38
	s_add_u32 s22, s6, s90
	s_addc_u32 s23, s7, s91
	s_sub_i32 s72, s22, s90
	s_sub_i32 s73, s10, s72
	s_cmp_lt_i32 s73, 1
	s_cbranch_scc1 .Lqu_done
	s_lshl_b32 s74, s73, 2
	s_cmp_gt_u32 s74, s38
	s_cbranch_scc1 .Lqu_half
	s_cmp_ge_u32 s90, s74
	s_cbranch_scc1 .Lqu_done
	s_and_b32 s101, s101, 7
	s_or_b32 s101, s101, 16
	s_mov_b32 s72, s90
	s_cmp_lt_u32 s72, s73
	s_cbranch_scc1 .Lqu_done
	s_sub_u32 s72, s72, s73
	s_and_b32 s101, s101, 7
	s_or_b32 s101, s101, 32
	s_cmp_lt_u32 s72, s73
	s_cbranch_scc1 .Lqu_adj
	s_sub_u32 s72, s72, s73
	s_and_b32 s101, s101, 7
	s_or_b32 s101, s101, 48
	s_cmp_lt_u32 s72, s73
	s_cbranch_scc1 .Lqu_adj
	s_sub_u32 s72, s72, s73
	s_and_b32 s101, s101, 7
	s_or_b32 s101, s101, 64
.Lqu_adj:
	s_sub_u32 s74, s90, s72
	s_sub_u32 s22, s22, s74
	s_subb_u32 s23, s23, 0
	s_branch .Lqu_done
.Lqu_half:
	s_lshl_b32 s74, s73, 1
	s_cmp_gt_u32 s74, s38
	s_cbranch_scc1 .Lqu_done
	s_cmp_lt_u32 s90, s73
	s_cbranch_scc0 .Lqu_second
	s_and_b32 s101, s101, 7
	s_or_b32 s101, s101, 80
	s_branch .Lqu_done
.Lqu_second:
	s_cmp_lt_u32 s90, s74
	s_cbranch_scc0 .Lqu_done
	s_sub_u32 s22, s22, s73
	s_subb_u32 s23, s23, 0
	s_and_b32 s101, s101, 7
	s_or_b32 s101, s101, 96

; template <class Epi, class Sched, bool ALIGN_EPI = false, bool SP2 = false>
; __device__ __forceinline__ void gemm_phase(PG8_LAS unsigned char* lds, const Gemm g, const Sched& S, const Epi& E) {
;     ...
;         const char* nA = has_next ? (const char*)g.A + (size_t)nxt.pm * tstep : cA; const char* nB = has_next ? (const char*)g.Bt + (size_t)nxt.pn * tstep : cB;
;         for (int t = 0; t < nt; t += 2) {
;             const bool last = (t == nt - 2);
;             const char* a1 = cA + (size_t)(t + 1) * kstep;
;             const char* a2 = last ? nA : cA + (size_t)(t + 2) * kstep; const char* b2 = last ? nB : cB + (size_t)(t + 2) * kstep;
;             const char* a3 = a2 + kstep; const char* b3 = b2 + kstep;
;     ...
; #pragma unroll
;         for (int a = 0; a < 2; ++a)
; #pragma unroll
;             for (int b = 0; b < 2; ++b)
; #pragma unroll
;                 for (int m = 0; m < 4; ++m)
; #pragma unroll
;                     for (int n = 0; n < 2; ++n) acc[a][b][m][n] = (f32x4){0.f, 0.f, 0.f, 0.f};
.LBB0_162:
	s_ashr_i32 s21, s20, 31
	s_lshl_b64 s[22:23], s[20:21], 19
	s_add_u32 s22, s46, s22
	s_addc_u32 s23, s47, s23
	s_and_b64 s[24:25], s[6:7], exec
	s_cselect_b32 s21, s23, s31
	s_cselect_b32 s27, s22, s30
	s_ashr_i32 s19, s18, 31
	s_lshl_b64 s[24:25], s[18:19], 19
	s_add_u32 s24, s48, s24
	s_addc_u32 s25, s49, s25
	s_and_b64 s[40:41], s[6:7], exec
	s_cselect_b32 s19, s25, s35
	s_cselect_b32 s50, s24, s34
	s_add_u32 s30, s30, 0x40080
	s_addc_u32 s31, s31, 0
	s_add_u32 s52, s34, 0x100
	v_mov_b32_e32 v2, 0
	s_addc_u32 s54, s35, 0
	s_mov_b32 s62, -2
	v_mov_b32_e32 v3, v2
	v_mov_b32_e32 v4, v2
	v_mov_b32_e32 v5, v2
	v_mov_b32_e32 v6, v2
	v_mov_b32_e32 v7, v2
	v_mov_b32_e32 v8, v2
	v_mov_b32_e32 v9, v2
	v_mov_b32_e32 v18, v2
	v_mov_b32_e32 v19, v2
	v_mov_b32_e32 v20, v2
	v_mov_b32_e32 v21, v2
	v_mov_b32_e32 v22, v2
	v_mov_b32_e32 v23, v2
	v_mov_b32_e32 v24, v2
	v_mov_b32_e32 v25, v2
	v_mov_b32_e32 v34, v2
	v_mov_b32_e32 v35, v2
	v_mov_b32_e32 v36, v2
	v_mov_b32_e32 v37, v2
	v_mov_b32_e32 v38, v2
	v_mov_b32_e32 v39, v2
	v_mov_b32_e32 v40, v2
	v_mov_b32_e32 v41, v2
	v_mov_b32_e32 v50, v2
	v_mov_b32_e32 v51, v2
	v_mov_b32_e32 v52, v2
	v_mov_b32_e32 v53, v2
	v_mov_b32_e32 v54, v2
	v_mov_b32_e32 v55, v2
	v_mov_b32_e32 v56, v2
	v_mov_b32_e32 v57, v2
	v_mov_b32_e32 v10, v2
	v_mov_b32_e32 v11, v2
	v_mov_b32_e32 v12, v2
	v_mov_b32_e32 v13, v2
	v_mov_b32_e32 v14, v2
	v_mov_b32_e32 v15, v2
	v_mov_b32_e32 v16, v2
	v_mov_b32_e32 v17, v2
	v_mov_b32_e32 v26, v2
	v_mov_b32_e32 v27, v2
	v_mov_b32_e32 v28, v2
	v_mov_b32_e32 v29, v2
	v_mov_b32_e32 v30, v2
	v_mov_b32_e32 v31, v2
	v_mov_b32_e32 v32, v2
	v_mov_b32_e32 v33, v2
	v_mov_b32_e32 v42, v2
	v_mov_b32_e32 v43, v2
	v_mov_b32_e32 v44, v2
	v_mov_b32_e32 v45, v2
	v_mov_b32_e32 v46, v2
	v_mov_b32_e32 v47, v2
	v_mov_b32_e32 v48, v2
	v_mov_b32_e32 v49, v2
	v_mov_b32_e32 v58, v2
	v_mov_b32_e32 v59, v2
	v_mov_b32_e32 v60, v2
	v_mov_b32_e32 v61, v2
	v_mov_b32_e32 v62, v2
	v_mov_b32_e32 v63, v2
	v_mov_b32_e32 v64, v2
	v_mov_b32_e32 v65, v2
	v_mov_b32_e32 v66, v2
	v_mov_b32_e32 v67, v2
	v_mov_b32_e32 v68, v2
	v_mov_b32_e32 v69, v2
	v_mov_b32_e32 v70, v2
	v_mov_b32_e32 v71, v2
	v_mov_b32_e32 v72, v2
	v_mov_b32_e32 v73, v2
	v_mov_b32_e32 v82, v2
	v_mov_b32_e32 v83, v2
	v_mov_b32_e32 v84, v2
	v_mov_b32_e32 v85, v2
	v_mov_b32_e32 v86, v2
	v_mov_b32_e32 v87, v2
	v_mov_b32_e32 v88, v2
	v_mov_b32_e32 v89, v2
	v_mov_b32_e32 v98, v2
	v_mov_b32_e32 v99, v2
	v_mov_b32_e32 v100, v2
	v_mov_b32_e32 v101, v2
	v_mov_b32_e32 v102, v2
	v_mov_b32_e32 v103, v2
	v_mov_b32_e32 v104, v2
	v_mov_b32_e32 v105, v2
	v_mov_b32_e32 v114, v2
	v_mov_b32_e32 v115, v2
	v_mov_b32_e32 v116, v2
	v_mov_b32_e32 v117, v2
	v_mov_b32_e32 v118, v2
	v_mov_b32_e32 v119, v2
	v_mov_b32_e32 v120, v2
	v_mov_b32_e32 v121, v2
	v_mov_b32_e32 v74, v2
	v_mov_b32_e32 v75, v2
	v_mov_b32_e32 v76, v2
	v_mov_b32_e32 v77, v2
	v_mov_b32_e32 v78, v2
	v_mov_b32_e32 v79, v2
	v_mov_b32_e32 v80, v2
	v_mov_b32_e32 v81, v2
	v_mov_b32_e32 v90, v2
	v_mov_b32_e32 v91, v2
	v_mov_b32_e32 v92, v2
	v_mov_b32_e32 v93, v2
	v_mov_b32_e32 v94, v2
	v_mov_b32_e32 v95, v2
	v_mov_b32_e32 v96, v2
	v_mov_b32_e32 v97, v2
	v_mov_b32_e32 v106, v2
	v_mov_b32_e32 v107, v2
	v_mov_b32_e32 v108, v2
	v_mov_b32_e32 v109, v2
	v_mov_b32_e32 v110, v2
	v_mov_b32_e32 v111, v2
	v_mov_b32_e32 v112, v2
	v_mov_b32_e32 v113, v2
	v_mov_b32_e32 v122, v2
	v_mov_b32_e32 v123, v2
	v_mov_b32_e32 v124, v2
	v_mov_b32_e32 v125, v2
	v_mov_b32_e32 v126, v2
	v_mov_b32_e32 v127, v2
	v_mov_b32_e32 v128, v2
	v_mov_b32_e32 v129, v2
	s_and_b32 s98, s101, 7
	s_cmp_lg_u32 s98, 0
	s_cbranch_scc0 .LBB0_163
	s_and_b32 s98, s101, 7
	s_cmp_eq_u32 s98, 1
	s_cbranch_scc1 .Lkuq_1
	s_and_b32 s98, s101, 7
	s_cmp_eq_u32 s98, 2
	s_cbranch_scc1 .Lkuq_2
	s_and_b32 s98, s101, 7
	s_cmp_eq_u32 s98, 3
	s_cbranch_scc1 .Lkuq_3
	s_and_b32 s98, s101, 7
	s_cmp_eq_u32 s98, 4
	s_cbranch_scc1 .Lkuq_4
	s_and_b32 s98, s101, 7
	s_cmp_eq_u32 s98, 5
	s_cbranch_scc1 .Lku_a0
	s_branch .Lku_a1

; #define PG8_STAGE(bufoff, gbase, voff) do { _Pragma("unroll") for (int _i = 0; _i < 2; ++_i) \
;         __builtin_amdgcn_global_load_lds((const unsigned*)((const char*)(gbase) + (voff)[_i]), (PG8_LAS unsigned*)(lds + (bufoff) + ldsw + _i * 8192), 16, 0, 0); } while (0)
; #define PG8_LDA(dst, b, h) do { _Pragma("unroll") for (int m = 0; m < 4; ++m) _Pragma("unroll") for (int k = 0; k < 2; ++k) dst[m][k] = *(const PG8_LAS bf16x8*)(lds + PG8_SA(b, h) + aoff + m * 2048 + k * 1024); } while (0)
; #define PG8_LDB(dst, b, h) do { _Pragma("unroll") for (int n = 0; n < 2; ++n) _Pragma("unroll") for (int k = 0; k < 2; ++k) dst[n][k] = *(const PG8_LAS bf16x8*)(lds + PG8_SB(b, h) + boff + n * 2048 + k * 1024); } while (0)
; #define PG8_MMA(ai, bj, At, Bt) do { __builtin_amdgcn_s_setprio(1); _Pragma("unroll") for (int m = 0; m < 4; ++m) _Pragma("unroll") for (int n = 0; n < 2; ++n) _Pragma("unroll") for (int k = 0; k < 2; ++k) \
;         acc[ai][bj][m][n] = __builtin_amdgcn_mfma_f32_16x16x32_bf16(Bt[n][k], At[m][k], acc[ai][bj][m][n], 0, 0, 0); __builtin_amdgcn_s_setprio(0); } while (0)
; #define PG8_WAIT_V(n) asm volatile("s_waitcnt vmcnt(" #n ")" ::: "memory")
; template <class Epi, class Sched, bool ALIGN_EPI = false, bool SP2 = false>
; __device__ __forceinline__ void gemm_phase(PG8_LAS unsigned char* lds, const Gemm g, const Sched& S, const Epi& E) {
;     ...
;             PG8_LDB(B0, 0, 0); PG8_LDB(B1, 0, 1); PG8_SCHED; PG8_LDA(At, 0, 0); PG8_STAGE(PG8_SA(1, 1), a1 + hstep, voffA);
;             PG8_WAIT_V(8); PG8_WAIT_L(0); PG8_BAR; PG8_MMA(0, 0, At, B0); PG8_MMA(0, 1, At, B1); PG8_BAR; PG8_SCHED;
;             PG8_LDA(At, 0, 1); PG8_STAGE(PG8_SB(0, 0), b2, voffB); PG8_STAGE(PG8_SB(0, 1), b2 + hstep, voffB); PG8_STAGE(PG8_SA(0, 0), a2, voffA);
;             PG8_WAIT_V(8); PG8_WAIT_L(0); PG8_BAR; PG8_MMA(1, 0, At, B0); PG8_MMA(1, 1, At, B1); PG8_BAR; PG8_SCHED;
;             PG8_LDB(B0, 1, 0); PG8_LDB(B1, 1, 1); PG8_SCHED; PG8_LDA(At, 1, 0); PG8_STAGE(PG8_SA(0, 1), a2 + hstep, voffA);
;             PG8_WAIT_V(8); PG8_WAIT_L(0); PG8_BAR; PG8_MMA(0, 0, At, B0); PG8_MMA(0, 1, At, B1); PG8_BAR; PG8_SCHED;
;             PG8_LDA(At, 1, 1); PG8_STAGE(PG8_SB(1, 0), b3, voffB); PG8_STAGE(PG8_SB(1, 1), b3 + hstep, voffB); PG8_STAGE(PG8_SA(1, 0), a3, voffA);
;             PG8_WAIT_V(8); PG8_WAIT_L(0); PG8_BAR; PG8_MMA(1, 0, At, B0); PG8_MMA(1, 1, At, B1); PG8_BAR; PG8_SCHED;
.Lku_a1:
	s_add_u32 s34, s30, 0xfffc0080
	s_addc_u32 s35, s31, -1
	s_add_i32 s71, 0, 0x10000
	s_cmp_eq_u32 s62, 12
	s_cselect_b32 s41, s21, s35
	s_cselect_b32 s40, s27, s34
	v_add_u32_e32 v155, s71, v145
	s_cselect_b32 s35, s19, s54
	s_cselect_b32 s34, s50, s52
	s_add_i32 s74, 0, 0x14000
	ds_read_b128 v[156:159], v155
	ds_read_b128 v[160:163], v155 offset:1024
	ds_read_b128 v[164:167], v155 offset:2048
	ds_read_b128 v[168:171], v155 offset:3072
	v_add_u32_e32 v155, s74, v145
	ds_read_b128 v[172:175], v155
	ds_read_b128 v[176:179], v155 offset:1024
	ds_read_b128 v[180:183], v155 offset:2048
	ds_read_b128 v[208:211], v155 offset:3072
	v_lshl_add_u64 v[202:203], s[30:31], 0, v[134:135]
	s_add_i32 m0, s29, 0xc000
	global_load_lds_dwordx4 v[202:203], off
	v_lshl_add_u64 v[202:203], s[30:31], 0, v[136:137]
	s_add_i32 m0, s29, 0xe000
	s_nop 0
	global_load_lds_dwordx4 v[202:203], off
	s_waitcnt vmcnt(6)
	s_waitcnt lgkmcnt(0)
	s_barrier
	s_setprio 1
	s_waitcnt lgkmcnt(0)
	s_setprio 0
	s_setprio 1
	s_setprio 0
	s_barrier
	s_add_i32 s71, s71, s80
	v_lshl_add_u64 v[202:203], s[34:35], 0, v[132:133]
	s_mov_b32 m0, s71
	ds_read_b128 v[212:215], v154 offset:16384
	ds_read_b128 v[216:219], v154 offset:17408
	ds_read_b128 v[220:223], v154 offset:18432
	ds_read_b128 v[224:227], v154 offset:19456
	ds_read_b128 v[228:231], v154 offset:20480
	ds_read_b128 v[232:235], v154 offset:21504
	ds_read_b128 v[236:239], v154 offset:22528
	ds_read_b128 v[240:243], v154 offset:23552
	global_load_lds_dwordx4 v[202:203], off
	s_add_i32 m0, s71, 0x2000
	s_add_u32 s72, s34, 0x40000
	v_lshl_add_u64 v[204:205], s[34:35], 0, v[130:131]
	s_addc_u32 s73, s35, 0
	s_add_i32 s71, s74, s80
	global_load_lds_dwordx4 v[204:205], off
	v_lshl_add_u64 v[244:245], s[72:73], 0, v[132:133]
	s_mov_b32 m0, s71
	v_lshl_add_u64 v[246:247], s[40:41], 0, v[130:131]
	global_load_lds_dwordx4 v[244:245], off
	v_lshl_add_u64 v[244:245], s[72:73], 0, v[130:131]
	s_add_i32 m0, s71, 0x2000
	s_nop 0
	global_load_lds_dwordx4 v[244:245], off
	v_lshl_add_u64 v[244:245], s[40:41], 0, v[132:133]
	s_mov_b32 m0, s29
	s_nop 0
	s_mov_b32 m0, s81
	s_nop 0
	s_waitcnt vmcnt(6)
	s_waitcnt lgkmcnt(0)
	s_barrier
	s_setprio 1
	s_waitcnt lgkmcnt(0)
	v_mfma_f32_16x16x32_bf16 v[62:65], v[156:159], v[212:215], v[62:65]
	v_mfma_f32_16x16x32_bf16 v[58:61], v[164:167], v[212:215], v[58:61]
	v_mfma_f32_16x16x32_bf16 v[46:49], v[156:159], v[220:223], v[46:49]
	v_mfma_f32_16x16x32_bf16 v[42:45], v[164:167], v[220:223], v[42:45]
	v_mfma_f32_16x16x32_bf16 v[30:33], v[156:159], v[228:231], v[30:33]
	v_mfma_f32_16x16x32_bf16 v[26:29], v[164:167], v[228:231], v[26:29]
	v_mfma_f32_16x16x32_bf16 v[14:17], v[156:159], v[236:239], v[14:17]
	v_mfma_f32_16x16x32_bf16 v[10:13], v[164:167], v[236:239], v[10:13]
	v_mfma_f32_16x16x32_bf16 v[62:65], v[160:163], v[216:219], v[62:65]
	v_mfma_f32_16x16x32_bf16 v[58:61], v[168:171], v[216:219], v[58:61]
	v_mfma_f32_16x16x32_bf16 v[46:49], v[160:163], v[224:227], v[46:49]
	v_mfma_f32_16x16x32_bf16 v[42:45], v[168:171], v[224:227], v[42:45]
	v_mfma_f32_16x16x32_bf16 v[30:33], v[160:163], v[232:235], v[30:33]
	v_mfma_f32_16x16x32_bf16 v[26:29], v[168:171], v[232:235], v[26:29]
	v_mfma_f32_16x16x32_bf16 v[14:17], v[160:163], v[240:243], v[14:17]
	v_mfma_f32_16x16x32_bf16 v[10:13], v[168:171], v[240:243], v[10:13]
	s_setprio 0
	s_setprio 1
	v_mfma_f32_16x16x32_bf16 v[54:57], v[172:175], v[212:215], v[54:57]
	v_mfma_f32_16x16x32_bf16 v[50:53], v[180:183], v[212:215], v[50:53]
	v_mfma_f32_16x16x32_bf16 v[38:41], v[172:175], v[220:223], v[38:41]
	v_mfma_f32_16x16x32_bf16 v[34:37], v[180:183], v[220:223], v[34:37]
	v_mfma_f32_16x16x32_bf16 v[22:25], v[172:175], v[228:231], v[22:25]
	v_mfma_f32_16x16x32_bf16 v[18:21], v[180:183], v[228:231], v[18:21]
	v_mfma_f32_16x16x32_bf16 v[6:9], v[172:175], v[236:239], v[6:9]
	v_mfma_f32_16x16x32_bf16 v[2:5], v[180:183], v[236:239], v[2:5]
	v_mfma_f32_16x16x32_bf16 v[54:57], v[176:179], v[216:219], v[54:57]
	v_mfma_f32_16x16x32_bf16 v[50:53], v[208:211], v[216:219], v[50:53]
	v_mfma_f32_16x16x32_bf16 v[38:41], v[176:179], v[224:227], v[38:41]
	v_mfma_f32_16x16x32_bf16 v[34:37], v[208:211], v[224:227], v[34:37]
	v_mfma_f32_16x16x32_bf16 v[22:25], v[176:179], v[232:235], v[22:25]
	v_mfma_f32_16x16x32_bf16 v[18:21], v[208:211], v[232:235], v[18:21]
	v_mfma_f32_16x16x32_bf16 v[6:9], v[176:179], v[240:243], v[6:9]
	v_mfma_f32_16x16x32_bf16 v[2:5], v[208:211], v[240:243], v[2:5]
	s_setprio 0
	s_barrier
	s_add_i32 s71, 0, 0x18000
	v_add_u32_e32 v155, s71, v145
	s_add_i32 s72, 0, 0x1c000
	ds_read_b128 v[156:159], v155
	ds_read_b128 v[160:163], v155 offset:1024
	ds_read_b128 v[164:167], v155 offset:2048
	ds_read_b128 v[168:171], v155 offset:3072
	v_add_u32_e32 v155, s72, v145
	ds_read_b128 v[172:175], v155
	ds_read_b128 v[176:179], v155 offset:1024
	ds_read_b128 v[180:183], v155 offset:2048
	ds_read_b128 v[208:211], v155 offset:3072
	s_add_u32 s40, s40, 0x40000
	s_addc_u32 s41, s41, 0
	s_mov_b32 m0, s82
	v_lshl_add_u64 v[248:249], s[40:41], 0, v[132:133]
	global_load_lds_dwordx4 v[248:249], off
	v_lshl_add_u64 v[248:249], s[40:41], 0, v[130:131]
	s_mov_b32 m0, s83
	s_nop 0
	global_load_lds_dwordx4 v[248:249], off
	s_waitcnt vmcnt(6)
	s_waitcnt lgkmcnt(0)
	s_barrier
	s_setprio 1
	s_waitcnt lgkmcnt(0)
	s_setprio 0
	s_setprio 1
	s_setprio 0
	s_barrier
; #define PG8_STAGE(bufoff, gbase, voff) do { _Pragma("unroll") for (int _i = 0; _i < 2; ++_i) \
;         __builtin_amdgcn_global_load_lds((const unsigned*)((const char*)(gbase) + (voff)[_i]), (PG8_LAS unsigned*)(lds + (bufoff) + ldsw + _i * 8192), 16, 0, 0); } while (0)
; #define PG8_LDA(dst, b, h) do { _Pragma("unroll") for (int m = 0; m < 4; ++m) _Pragma("unroll") for (int k = 0; k < 2; ++k) dst[m][k] = *(const PG8_LAS bf16x8*)(lds + PG8_SA(b, h) + aoff + m * 2048 + k * 1024); } while (0)
; #define PG8_LDB(dst, b, h) do { _Pragma("unroll") for (int n = 0; n < 2; ++n) _Pragma("unroll") for (int k = 0; k < 2; ++k) dst[n][k] = *(const PG8_LAS bf16x8*)(lds + PG8_SB(b, h) + boff + n * 2048 + k * 1024); } while (0)
; #define PG8_MMA(ai, bj, At, Bt) do { __builtin_amdgcn_s_setprio(1); _Pragma("unroll") for (int m = 0; m < 4; ++m) _Pragma("unroll") for (int n = 0; n < 2; ++n) _Pragma("unroll") for (int k = 0; k < 2; ++k) \
;         acc[ai][bj][m][n] = __builtin_amdgcn_mfma_f32_16x16x32_bf16(Bt[n][k], At[m][k], acc[ai][bj][m][n], 0, 0, 0); __builtin_amdgcn_s_setprio(0); } while (0)
; #define PG8_WAIT_V(n) asm volatile("s_waitcnt vmcnt(" #n ")" ::: "memory")
; template <class Epi, class Sched, bool ALIGN_EPI = false, bool SP2 = false>
; __device__ __forceinline__ void gemm_phase(PG8_LAS unsigned char* lds, const Gemm g, const Sched& S, const Epi& E) {
;     ...
;             PG8_LDB(B0, 0, 0); PG8_LDB(B1, 0, 1); PG8_SCHED; PG8_LDA(At, 0, 0); PG8_STAGE(PG8_SA(1, 1), a1 + hstep, voffA);
;             PG8_WAIT_V(8); PG8_WAIT_L(0); PG8_BAR; PG8_MMA(0, 0, At, B0); PG8_MMA(0, 1, At, B1); PG8_BAR; PG8_SCHED;
;             PG8_LDA(At, 0, 1); PG8_STAGE(PG8_SB(0, 0), b2, voffB); PG8_STAGE(PG8_SB(0, 1), b2 + hstep, voffB); PG8_STAGE(PG8_SA(0, 0), a2, voffA);
;             PG8_WAIT_V(8); PG8_WAIT_L(0); PG8_BAR; PG8_MMA(1, 0, At, B0); PG8_MMA(1, 1, At, B1); PG8_BAR; PG8_SCHED;
;             PG8_LDB(B0, 1, 0); PG8_LDB(B1, 1, 1); PG8_SCHED; PG8_LDA(At, 1, 0); PG8_STAGE(PG8_SA(0, 1), a2 + hstep, voffA);
;             PG8_WAIT_V(8); PG8_WAIT_L(0); PG8_BAR; PG8_MMA(0, 0, At, B0); PG8_MMA(0, 1, At, B1); PG8_BAR; PG8_SCHED;
;             PG8_LDA(At, 1, 1); PG8_STAGE(PG8_SB(1, 0), b3, voffB); PG8_STAGE(PG8_SB(1, 1), b3 + hstep, voffB); PG8_STAGE(PG8_SA(1, 0), a3, voffA);
;             PG8_WAIT_V(8); PG8_WAIT_L(0); PG8_BAR; PG8_MMA(1, 0, At, B0); PG8_MMA(1, 1, At, B1); PG8_BAR; PG8_SCHED;
	s_add_i32 s40, s71, s80
	v_lshl_add_u64 v[202:203], v[202:203], 0, s[66:67]
	s_mov_b32 m0, s40
	ds_read_b128 v[212:215], v154 offset:49152
	ds_read_b128 v[216:219], v154 offset:50176
	ds_read_b128 v[220:223], v154 offset:51200
	ds_read_b128 v[224:227], v154 offset:52224
	ds_read_b128 v[228:231], v154 offset:53248
	ds_read_b128 v[232:235], v154 offset:54272
	ds_read_b128 v[236:239], v154 offset:55296
	ds_read_b128 v[240:243], v154 offset:56320
	global_load_lds_dwordx4 v[202:203], off
	s_add_i32 m0, s40, 0x2000
	s_add_u32 s34, s34, 0x40080
	v_lshl_add_u64 v[202:203], v[204:205], 0, s[66:67]
	s_addc_u32 s35, s35, 0
	s_add_i32 s40, s72, s80
	global_load_lds_dwordx4 v[202:203], off
	v_lshl_add_u64 v[202:203], s[34:35], 0, v[132:133]
	s_mov_b32 m0, s40
	s_nop 0
	global_load_lds_dwordx4 v[202:203], off
	v_lshl_add_u64 v[202:203], s[34:35], 0, v[130:131]
	s_add_i32 m0, s40, 0x2000
	s_nop 0
	global_load_lds_dwordx4 v[202:203], off
	v_lshl_add_u64 v[202:203], v[244:245], 0, s[66:67]
	s_mov_b32 m0, s84
	s_nop 0
	v_lshl_add_u64 v[202:203], v[246:247], 0, s[66:67]
	s_mov_b32 m0, s85
	s_nop 0
	s_waitcnt vmcnt(6)
	s_waitcnt lgkmcnt(0)
	s_barrier
	s_setprio 1
	s_waitcnt lgkmcnt(0)
	v_mfma_f32_16x16x32_bf16 v[62:65], v[156:159], v[212:215], v[62:65]
	v_mfma_f32_16x16x32_bf16 v[58:61], v[164:167], v[212:215], v[58:61]
	v_mfma_f32_16x16x32_bf16 v[46:49], v[156:159], v[220:223], v[46:49]
	v_mfma_f32_16x16x32_bf16 v[42:45], v[164:167], v[220:223], v[42:45]
	v_mfma_f32_16x16x32_bf16 v[30:33], v[156:159], v[228:231], v[30:33]
	v_mfma_f32_16x16x32_bf16 v[26:29], v[164:167], v[228:231], v[26:29]
	v_mfma_f32_16x16x32_bf16 v[14:17], v[156:159], v[236:239], v[14:17]
	v_mfma_f32_16x16x32_bf16 v[10:13], v[164:167], v[236:239], v[10:13]
	v_mfma_f32_16x16x32_bf16 v[62:65], v[160:163], v[216:219], v[62:65]
	v_mfma_f32_16x16x32_bf16 v[58:61], v[168:171], v[216:219], v[58:61]
	v_mfma_f32_16x16x32_bf16 v[46:49], v[160:163], v[224:227], v[46:49]
	v_mfma_f32_16x16x32_bf16 v[42:45], v[168:171], v[224:227], v[42:45]
	v_mfma_f32_16x16x32_bf16 v[30:33], v[160:163], v[232:235], v[30:33]
	v_mfma_f32_16x16x32_bf16 v[26:29], v[168:171], v[232:235], v[26:29]
	v_mfma_f32_16x16x32_bf16 v[14:17], v[160:163], v[240:243], v[14:17]
	v_mfma_f32_16x16x32_bf16 v[10:13], v[168:171], v[240:243], v[10:13]
	s_setprio 0
	s_setprio 1
	v_mfma_f32_16x16x32_bf16 v[54:57], v[172:175], v[212:215], v[54:57]
	v_mfma_f32_16x16x32_bf16 v[50:53], v[180:183], v[212:215], v[50:53]
	v_mfma_f32_16x16x32_bf16 v[38:41], v[172:175], v[220:223], v[38:41]
	v_mfma_f32_16x16x32_bf16 v[34:37], v[180:183], v[220:223], v[34:37]
	v_mfma_f32_16x16x32_bf16 v[22:25], v[172:175], v[228:231], v[22:25]
	v_mfma_f32_16x16x32_bf16 v[18:21], v[180:183], v[228:231], v[18:21]
	v_mfma_f32_16x16x32_bf16 v[6:9], v[172:175], v[236:239], v[6:9]
	v_mfma_f32_16x16x32_bf16 v[2:5], v[180:183], v[236:239], v[2:5]
	v_mfma_f32_16x16x32_bf16 v[54:57], v[176:179], v[216:219], v[54:57]
	v_mfma_f32_16x16x32_bf16 v[50:53], v[208:211], v[216:219], v[50:53]
	v_mfma_f32_16x16x32_bf16 v[38:41], v[176:179], v[224:227], v[38:41]
	v_mfma_f32_16x16x32_bf16 v[34:37], v[208:211], v[224:227], v[34:37]
	v_mfma_f32_16x16x32_bf16 v[22:25], v[176:179], v[232:235], v[22:25]
	v_mfma_f32_16x16x32_bf16 v[18:21], v[208:211], v[232:235], v[18:21]
	v_mfma_f32_16x16x32_bf16 v[6:9], v[176:179], v[240:243], v[6:9]
	v_mfma_f32_16x16x32_bf16 v[2:5], v[208:211], v[240:243], v[2:5]
	s_setprio 0
	s_barrier
	s_add_i32 s62, s62, 2
	s_add_u32 s30, s30, 0x100
	s_addc_u32 s31, s31, 0
	s_add_u32 s52, s52, 0x100
	s_addc_u32 s54, s54, 0
	s_cmp_gt_u32 s62, 13
	s_cbranch_scc0 .Lku_a1
	s_branch .Lku_exit
.Lkuq_1:
	s_add_u32 s34, s30, 0xfffc0080
	s_addc_u32 s35, s31, -1
	s_add_i32 s71, 0, 0x10000
	s_cmp_eq_u32 s62, 12
	s_cselect_b32 s41, s21, s35
	s_cselect_b32 s40, s27, s34
	v_add_u32_e32 v155, s71, v145
	s_cselect_b32 s35, s19, s54
	s_cselect_b32 s34, s50, s52
	s_add_i32 s74, 0, 0x14000
	ds_read_b128 v[156:159], v155
	ds_read_b128 v[160:163], v155 offset:1024
	ds_read_b128 v[164:167], v155 offset:2048
	ds_read_b128 v[168:171], v155 offset:3072
	v_add_u32_e32 v155, s74, v145
	v_lshl_add_u64 v[202:203], s[30:31], 0, v[134:135]
	s_add_i32 m0, s29, 0xc000
	ds_read_b128 v[212:215], v154
	ds_read_b128 v[216:219], v154 offset:1024
	ds_read_b128 v[220:223], v154 offset:2048
	ds_read_b128 v[224:227], v154 offset:3072
	ds_read_b128 v[228:231], v154 offset:4096
	ds_read_b128 v[232:235], v154 offset:5120
	ds_read_b128 v[236:239], v154 offset:6144
	ds_read_b128 v[240:243], v154 offset:7168
	v_lshl_add_u64 v[202:203], s[30:31], 0, v[136:137]
	s_add_i32 m0, s29, 0xe000
	s_nop 0
	s_waitcnt vmcnt(4)
	s_waitcnt lgkmcnt(0)
	s_barrier
	s_setprio 1
	s_waitcnt lgkmcnt(0)
	v_mfma_f32_16x16x32_bf16 v[126:129], v[156:159], v[212:215], v[126:129]
	v_mfma_f32_16x16x32_bf16 v[122:125], v[164:167], v[212:215], v[122:125]
	v_mfma_f32_16x16x32_bf16 v[110:113], v[156:159], v[220:223], v[110:113]
	v_mfma_f32_16x16x32_bf16 v[106:109], v[164:167], v[220:223], v[106:109]
	v_mfma_f32_16x16x32_bf16 v[94:97], v[156:159], v[228:231], v[94:97]
	v_mfma_f32_16x16x32_bf16 v[90:93], v[164:167], v[228:231], v[90:93]
	v_mfma_f32_16x16x32_bf16 v[78:81], v[156:159], v[236:239], v[78:81]
	v_mfma_f32_16x16x32_bf16 v[74:77], v[164:167], v[236:239], v[74:77]
	v_mfma_f32_16x16x32_bf16 v[126:129], v[160:163], v[216:219], v[126:129]
	v_mfma_f32_16x16x32_bf16 v[122:125], v[168:171], v[216:219], v[122:125]
	v_mfma_f32_16x16x32_bf16 v[110:113], v[160:163], v[224:227], v[110:113]
	v_mfma_f32_16x16x32_bf16 v[106:109], v[168:171], v[224:227], v[106:109]
	v_mfma_f32_16x16x32_bf16 v[94:97], v[160:163], v[232:235], v[94:97]
	v_mfma_f32_16x16x32_bf16 v[90:93], v[168:171], v[232:235], v[90:93]
	v_mfma_f32_16x16x32_bf16 v[78:81], v[160:163], v[240:243], v[78:81]
	v_mfma_f32_16x16x32_bf16 v[74:77], v[168:171], v[240:243], v[74:77]
	s_setprio 0
	s_setprio 1
	s_setprio 0
	s_barrier
; #define PG8_STAGE(bufoff, gbase, voff) do { _Pragma("unroll") for (int _i = 0; _i < 2; ++_i) \
;         __builtin_amdgcn_global_load_lds((const unsigned*)((const char*)(gbase) + (voff)[_i]), (PG8_LAS unsigned*)(lds + (bufoff) + ldsw + _i * 8192), 16, 0, 0); } while (0)
; #define PG8_LDA(dst, b, h) do { _Pragma("unroll") for (int m = 0; m < 4; ++m) _Pragma("unroll") for (int k = 0; k < 2; ++k) dst[m][k] = *(const PG8_LAS bf16x8*)(lds + PG8_SA(b, h) + aoff + m * 2048 + k * 1024); } while (0)
; #define PG8_LDB(dst, b, h) do { _Pragma("unroll") for (int n = 0; n < 2; ++n) _Pragma("unroll") for (int k = 0; k < 2; ++k) dst[n][k] = *(const PG8_LAS bf16x8*)(lds + PG8_SB(b, h) + boff + n * 2048 + k * 1024); } while (0)
; #define PG8_MMA(ai, bj, At, Bt) do { __builtin_amdgcn_s_setprio(1); _Pragma("unroll") for (int m = 0; m < 4; ++m) _Pragma("unroll") for (int n = 0; n < 2; ++n) _Pragma("unroll") for (int k = 0; k < 2; ++k) \
;         acc[ai][bj][m][n] = __builtin_amdgcn_mfma_f32_16x16x32_bf16(Bt[n][k], At[m][k], acc[ai][bj][m][n], 0, 0, 0); __builtin_amdgcn_s_setprio(0); } while (0)
; #define PG8_WAIT_V(n) asm volatile("s_waitcnt vmcnt(" #n ")" ::: "memory")
; template <class Epi, class Sched, bool ALIGN_EPI = false, bool SP2 = false>
; __device__ __forceinline__ void gemm_phase(PG8_LAS unsigned char* lds, const Gemm g, const Sched& S, const Epi& E) {
;     ...
;             PG8_LDB(B0, 0, 0); PG8_LDB(B1, 0, 1); PG8_SCHED; PG8_LDA(At, 0, 0); PG8_STAGE(PG8_SA(1, 1), a1 + hstep, voffA);
;             PG8_WAIT_V(8); PG8_WAIT_L(0); PG8_BAR; PG8_MMA(0, 0, At, B0); PG8_MMA(0, 1, At, B1); PG8_BAR; PG8_SCHED;
;             PG8_LDA(At, 0, 1); PG8_STAGE(PG8_SB(0, 0), b2, voffB); PG8_STAGE(PG8_SB(0, 1), b2 + hstep, voffB); PG8_STAGE(PG8_SA(0, 0), a2, voffA);
;             PG8_WAIT_V(8); PG8_WAIT_L(0); PG8_BAR; PG8_MMA(1, 0, At, B0); PG8_MMA(1, 1, At, B1); PG8_BAR; PG8_SCHED;
;             PG8_LDB(B0, 1, 0); PG8_LDB(B1, 1, 1); PG8_SCHED; PG8_LDA(At, 1, 0); PG8_STAGE(PG8_SA(0, 1), a2 + hstep, voffA);
;             PG8_WAIT_V(8); PG8_WAIT_L(0); PG8_BAR; PG8_MMA(0, 0, At, B0); PG8_MMA(0, 1, At, B1); PG8_BAR; PG8_SCHED;
;             PG8_LDA(At, 1, 1); PG8_STAGE(PG8_SB(1, 0), b3, voffB); PG8_STAGE(PG8_SB(1, 1), b3 + hstep, voffB); PG8_STAGE(PG8_SA(1, 0), a3, voffA);
;             PG8_WAIT_V(8); PG8_WAIT_L(0); PG8_BAR; PG8_MMA(1, 0, At, B0); PG8_MMA(1, 1, At, B1); PG8_BAR; PG8_SCHED;
	s_add_i32 s71, s71, s80
	v_lshl_add_u64 v[202:203], s[34:35], 0, v[132:133]
	s_mov_b32 m0, s71
	global_load_lds_dwordx4 v[202:203], off
	s_add_i32 m0, s71, 0x2000
	s_add_u32 s72, s34, 0x40000
	v_lshl_add_u64 v[204:205], s[34:35], 0, v[130:131]
	s_addc_u32 s73, s35, 0
	s_add_i32 s71, s74, s80
	global_load_lds_dwordx4 v[204:205], off
	v_lshl_add_u64 v[244:245], s[72:73], 0, v[132:133]
	s_mov_b32 m0, s71
	v_lshl_add_u64 v[246:247], s[40:41], 0, v[130:131]
	v_lshl_add_u64 v[244:245], s[72:73], 0, v[130:131]
	s_add_i32 m0, s71, 0x2000
	s_nop 0
	v_lshl_add_u64 v[244:245], s[40:41], 0, v[132:133]
	s_mov_b32 m0, s29
	s_nop 0
	global_load_lds_dwordx4 v[244:245], off
	s_mov_b32 m0, s81
	s_nop 0
	global_load_lds_dwordx4 v[246:247], off
	s_waitcnt vmcnt(4)
	s_waitcnt lgkmcnt(0)
	s_barrier
	s_setprio 1
	s_waitcnt lgkmcnt(0)
	s_setprio 0
	s_setprio 1
	s_setprio 0
	s_barrier
	s_add_i32 s71, 0, 0x18000
	v_add_u32_e32 v155, s71, v145
	s_add_i32 s72, 0, 0x1c000
	ds_read_b128 v[156:159], v155
	ds_read_b128 v[160:163], v155 offset:1024
	ds_read_b128 v[164:167], v155 offset:2048
	ds_read_b128 v[168:171], v155 offset:3072
	v_add_u32_e32 v155, s72, v145
	s_add_u32 s40, s40, 0x40000
	s_addc_u32 s41, s41, 0
	s_mov_b32 m0, s82
	v_lshl_add_u64 v[248:249], s[40:41], 0, v[132:133]
	ds_read_b128 v[212:215], v154 offset:32768
	ds_read_b128 v[216:219], v154 offset:33792
	ds_read_b128 v[220:223], v154 offset:34816
	ds_read_b128 v[224:227], v154 offset:35840
	ds_read_b128 v[228:231], v154 offset:36864
	ds_read_b128 v[232:235], v154 offset:37888
	ds_read_b128 v[236:239], v154 offset:38912
	ds_read_b128 v[240:243], v154 offset:39936
	v_lshl_add_u64 v[248:249], s[40:41], 0, v[130:131]
	s_mov_b32 m0, s83
	s_nop 0
	s_waitcnt vmcnt(4)
	s_waitcnt lgkmcnt(0)
	s_barrier
	s_setprio 1
	s_waitcnt lgkmcnt(0)
	v_mfma_f32_16x16x32_bf16 v[126:129], v[156:159], v[212:215], v[126:129]
	v_mfma_f32_16x16x32_bf16 v[122:125], v[164:167], v[212:215], v[122:125]
	v_mfma_f32_16x16x32_bf16 v[110:113], v[156:159], v[220:223], v[110:113]
	v_mfma_f32_16x16x32_bf16 v[106:109], v[164:167], v[220:223], v[106:109]
	v_mfma_f32_16x16x32_bf16 v[94:97], v[156:159], v[228:231], v[94:97]
	v_mfma_f32_16x16x32_bf16 v[90:93], v[164:167], v[228:231], v[90:93]
	v_mfma_f32_16x16x32_bf16 v[78:81], v[156:159], v[236:239], v[78:81]
	v_mfma_f32_16x16x32_bf16 v[74:77], v[164:167], v[236:239], v[74:77]
	v_mfma_f32_16x16x32_bf16 v[126:129], v[160:163], v[216:219], v[126:129]
	v_mfma_f32_16x16x32_bf16 v[122:125], v[168:171], v[216:219], v[122:125]
	v_mfma_f32_16x16x32_bf16 v[110:113], v[160:163], v[224:227], v[110:113]
	v_mfma_f32_16x16x32_bf16 v[106:109], v[168:171], v[224:227], v[106:109]
	v_mfma_f32_16x16x32_bf16 v[94:97], v[160:163], v[232:235], v[94:97]
	v_mfma_f32_16x16x32_bf16 v[90:93], v[168:171], v[232:235], v[90:93]
	v_mfma_f32_16x16x32_bf16 v[78:81], v[160:163], v[240:243], v[78:81]
	v_mfma_f32_16x16x32_bf16 v[74:77], v[168:171], v[240:243], v[74:77]
	s_setprio 0
	s_setprio 1
	s_setprio 0
	s_barrier
	s_add_i32 s40, s71, s80
	v_lshl_add_u64 v[202:203], v[202:203], 0, s[66:67]
	s_mov_b32 m0, s40
	global_load_lds_dwordx4 v[202:203], off
	s_add_i32 m0, s40, 0x2000
	s_add_u32 s34, s34, 0x40080
	v_lshl_add_u64 v[202:203], v[204:205], 0, s[66:67]
	s_addc_u32 s35, s35, 0
	s_add_i32 s40, s72, s80
	global_load_lds_dwordx4 v[202:203], off
	v_lshl_add_u64 v[202:203], s[34:35], 0, v[132:133]
	s_mov_b32 m0, s40
	s_nop 0
	v_lshl_add_u64 v[202:203], s[34:35], 0, v[130:131]
	s_add_i32 m0, s40, 0x2000
	s_nop 0
	v_lshl_add_u64 v[202:203], v[244:245], 0, s[66:67]
	s_mov_b32 m0, s84
	s_nop 0
	global_load_lds_dwordx4 v[202:203], off
	v_lshl_add_u64 v[202:203], v[246:247], 0, s[66:67]
	s_mov_b32 m0, s85
	s_nop 0
	global_load_lds_dwordx4 v[202:203], off
	s_waitcnt vmcnt(4)
	s_waitcnt lgkmcnt(0)
	s_barrier
	s_setprio 1
	s_waitcnt lgkmcnt(0)
	s_setprio 0
	s_setprio 1
	s_setprio 0
	s_barrier
	s_add_i32 s62, s62, 2
	s_add_u32 s30, s30, 0x100
	s_addc_u32 s31, s31, 0
	s_add_u32 s52, s52, 0x100
	s_addc_u32 s54, s54, 0
	s_cmp_gt_u32 s62, 13
	s_cbranch_scc0 .Lkuq_1
	s_branch .Lku_exit
.Lkuq_2:
	s_add_u32 s34, s30, 0xfffc0080
	s_addc_u32 s35, s31, -1
	s_add_i32 s71, 0, 0x10000
	s_cmp_eq_u32 s62, 12
	s_cselect_b32 s41, s21, s35
	s_cselect_b32 s40, s27, s34
	v_add_u32_e32 v155, s71, v145
	s_cselect_b32 s35, s19, s54
	s_cselect_b32 s34, s50, s52
	s_add_i32 s74, 0, 0x14000
	ds_read_b128 v[156:159], v155
	ds_read_b128 v[160:163], v155 offset:1024
	ds_read_b128 v[164:167], v155 offset:2048
	ds_read_b128 v[168:171], v155 offset:3072
	v_add_u32_e32 v155, s74, v145
	v_lshl_add_u64 v[202:203], s[30:31], 0, v[134:135]
	s_add_i32 m0, s29, 0xc000
	global_load_lds_dwordx4 v[202:203], off
	v_lshl_add_u64 v[202:203], s[30:31], 0, v[136:137]
	s_add_i32 m0, s29, 0xe000
	s_nop 0
	global_load_lds_dwordx4 v[202:203], off
	s_waitcnt vmcnt(4)
	s_waitcnt lgkmcnt(0)
	s_barrier
	s_setprio 1
	s_waitcnt lgkmcnt(0)
	s_setprio 0
	s_setprio 1
	s_setprio 0
	s_barrier
	s_add_i32 s71, s71, s80
	v_lshl_add_u64 v[202:203], s[34:35], 0, v[132:133]
	s_mov_b32 m0, s71
	ds_read_b128 v[212:215], v154 offset:16384
	ds_read_b128 v[216:219], v154 offset:17408
	ds_read_b128 v[220:223], v154 offset:18432
	ds_read_b128 v[224:227], v154 offset:19456
	ds_read_b128 v[228:231], v154 offset:20480
	ds_read_b128 v[232:235], v154 offset:21504
	ds_read_b128 v[236:239], v154 offset:22528
	ds_read_b128 v[240:243], v154 offset:23552
	global_load_lds_dwordx4 v[202:203], off
	s_add_i32 m0, s71, 0x2000
	s_add_u32 s72, s34, 0x40000
	v_lshl_add_u64 v[204:205], s[34:35], 0, v[130:131]
	s_addc_u32 s73, s35, 0
	s_add_i32 s71, s74, s80
	global_load_lds_dwordx4 v[204:205], off
	v_lshl_add_u64 v[244:245], s[72:73], 0, v[132:133]
	s_mov_b32 m0, s71
	v_lshl_add_u64 v[246:247], s[40:41], 0, v[130:131]
	v_lshl_add_u64 v[244:245], s[72:73], 0, v[130:131]
	s_add_i32 m0, s71, 0x2000
	s_nop 0
	v_lshl_add_u64 v[244:245], s[40:41], 0, v[132:133]
	s_mov_b32 m0, s29
	s_nop 0
	s_mov_b32 m0, s81
	s_nop 0
	s_waitcnt vmcnt(4)
	s_waitcnt lgkmcnt(0)
	s_barrier
; #define PG8_STAGE(bufoff, gbase, voff) do { _Pragma("unroll") for (int _i = 0; _i < 2; ++_i) \
;         __builtin_amdgcn_global_load_lds((const unsigned*)((const char*)(gbase) + (voff)[_i]), (PG8_LAS unsigned*)(lds + (bufoff) + ldsw + _i * 8192), 16, 0, 0); } while (0)
; #define PG8_LDA(dst, b, h) do { _Pragma("unroll") for (int m = 0; m < 4; ++m) _Pragma("unroll") for (int k = 0; k < 2; ++k) dst[m][k] = *(const PG8_LAS bf16x8*)(lds + PG8_SA(b, h) + aoff + m * 2048 + k * 1024); } while (0)
; #define PG8_LDB(dst, b, h) do { _Pragma("unroll") for (int n = 0; n < 2; ++n) _Pragma("unroll") for (int k = 0; k < 2; ++k) dst[n][k] = *(const PG8_LAS bf16x8*)(lds + PG8_SB(b, h) + boff + n * 2048 + k * 1024); } while (0)
; #define PG8_MMA(ai, bj, At, Bt) do { __builtin_amdgcn_s_setprio(1); _Pragma("unroll") for (int m = 0; m < 4; ++m) _Pragma("unroll") for (int n = 0; n < 2; ++n) _Pragma("unroll") for (int k = 0; k < 2; ++k) \
;         acc[ai][bj][m][n] = __builtin_amdgcn_mfma_f32_16x16x32_bf16(Bt[n][k], At[m][k], acc[ai][bj][m][n], 0, 0, 0); __builtin_amdgcn_s_setprio(0); } while (0)
; #define PG8_WAIT_V(n) asm volatile("s_waitcnt vmcnt(" #n ")" ::: "memory")
; template <class Epi, class Sched, bool ALIGN_EPI = false, bool SP2 = false>
; __device__ __forceinline__ void gemm_phase(PG8_LAS unsigned char* lds, const Gemm g, const Sched& S, const Epi& E) {
;     ...
;             PG8_LDB(B0, 0, 0); PG8_LDB(B1, 0, 1); PG8_SCHED; PG8_LDA(At, 0, 0); PG8_STAGE(PG8_SA(1, 1), a1 + hstep, voffA);
;             PG8_WAIT_V(8); PG8_WAIT_L(0); PG8_BAR; PG8_MMA(0, 0, At, B0); PG8_MMA(0, 1, At, B1); PG8_BAR; PG8_SCHED;
;             PG8_LDA(At, 0, 1); PG8_STAGE(PG8_SB(0, 0), b2, voffB); PG8_STAGE(PG8_SB(0, 1), b2 + hstep, voffB); PG8_STAGE(PG8_SA(0, 0), a2, voffA);
;             PG8_WAIT_V(8); PG8_WAIT_L(0); PG8_BAR; PG8_MMA(1, 0, At, B0); PG8_MMA(1, 1, At, B1); PG8_BAR; PG8_SCHED;
;             PG8_LDB(B0, 1, 0); PG8_LDB(B1, 1, 1); PG8_SCHED; PG8_LDA(At, 1, 0); PG8_STAGE(PG8_SA(0, 1), a2 + hstep, voffA);
;             PG8_WAIT_V(8); PG8_WAIT_L(0); PG8_BAR; PG8_MMA(0, 0, At, B0); PG8_MMA(0, 1, At, B1); PG8_BAR; PG8_SCHED;
;             PG8_LDA(At, 1, 1); PG8_STAGE(PG8_SB(1, 0), b3, voffB); PG8_STAGE(PG8_SB(1, 1), b3 + hstep, voffB); PG8_STAGE(PG8_SA(1, 0), a3, voffA);
;             PG8_WAIT_V(8); PG8_WAIT_L(0); PG8_BAR; PG8_MMA(1, 0, At, B0); PG8_MMA(1, 1, At, B1); PG8_BAR; PG8_SCHED;
	s_setprio 1
	s_waitcnt lgkmcnt(0)
	v_mfma_f32_16x16x32_bf16 v[62:65], v[156:159], v[212:215], v[62:65]
	v_mfma_f32_16x16x32_bf16 v[58:61], v[164:167], v[212:215], v[58:61]
	v_mfma_f32_16x16x32_bf16 v[46:49], v[156:159], v[220:223], v[46:49]
	v_mfma_f32_16x16x32_bf16 v[42:45], v[164:167], v[220:223], v[42:45]
	v_mfma_f32_16x16x32_bf16 v[30:33], v[156:159], v[228:231], v[30:33]
	v_mfma_f32_16x16x32_bf16 v[26:29], v[164:167], v[228:231], v[26:29]
	v_mfma_f32_16x16x32_bf16 v[14:17], v[156:159], v[236:239], v[14:17]
	v_mfma_f32_16x16x32_bf16 v[10:13], v[164:167], v[236:239], v[10:13]
	v_mfma_f32_16x16x32_bf16 v[62:65], v[160:163], v[216:219], v[62:65]
	v_mfma_f32_16x16x32_bf16 v[58:61], v[168:171], v[216:219], v[58:61]
	v_mfma_f32_16x16x32_bf16 v[46:49], v[160:163], v[224:227], v[46:49]
	v_mfma_f32_16x16x32_bf16 v[42:45], v[168:171], v[224:227], v[42:45]
	v_mfma_f32_16x16x32_bf16 v[30:33], v[160:163], v[232:235], v[30:33]
	v_mfma_f32_16x16x32_bf16 v[26:29], v[168:171], v[232:235], v[26:29]
	v_mfma_f32_16x16x32_bf16 v[14:17], v[160:163], v[240:243], v[14:17]
	v_mfma_f32_16x16x32_bf16 v[10:13], v[168:171], v[240:243], v[10:13]
	s_setprio 0
	s_setprio 1
	s_setprio 0
	s_barrier
	s_add_i32 s71, 0, 0x18000
	v_add_u32_e32 v155, s71, v145
	s_add_i32 s72, 0, 0x1c000
	ds_read_b128 v[156:159], v155
	ds_read_b128 v[160:163], v155 offset:1024
	ds_read_b128 v[164:167], v155 offset:2048
	ds_read_b128 v[168:171], v155 offset:3072
	v_add_u32_e32 v155, s72, v145
	s_add_u32 s40, s40, 0x40000
	s_addc_u32 s41, s41, 0
	s_mov_b32 m0, s82
	v_lshl_add_u64 v[248:249], s[40:41], 0, v[132:133]
	global_load_lds_dwordx4 v[248:249], off
	v_lshl_add_u64 v[248:249], s[40:41], 0, v[130:131]
	s_mov_b32 m0, s83
	s_nop 0
	global_load_lds_dwordx4 v[248:249], off
	s_waitcnt vmcnt(4)
	s_waitcnt lgkmcnt(0)
	s_barrier
	s_setprio 1
	s_waitcnt lgkmcnt(0)
	s_setprio 0
	s_setprio 1
	s_setprio 0
	s_barrier
	s_add_i32 s40, s71, s80
	v_lshl_add_u64 v[202:203], v[202:203], 0, s[66:67]
	s_mov_b32 m0, s40
	ds_read_b128 v[212:215], v154 offset:49152
	ds_read_b128 v[216:219], v154 offset:50176
	ds_read_b128 v[220:223], v154 offset:51200
	ds_read_b128 v[224:227], v154 offset:52224
	ds_read_b128 v[228:231], v154 offset:53248
	ds_read_b128 v[232:235], v154 offset:54272
	ds_read_b128 v[236:239], v154 offset:55296
	ds_read_b128 v[240:243], v154 offset:56320
	global_load_lds_dwordx4 v[202:203], off
	s_add_i32 m0, s40, 0x2000
	s_add_u32 s34, s34, 0x40080
	v_lshl_add_u64 v[202:203], v[204:205], 0, s[66:67]
	s_addc_u32 s35, s35, 0
	s_add_i32 s40, s72, s80
	global_load_lds_dwordx4 v[202:203], off
	v_lshl_add_u64 v[202:203], s[34:35], 0, v[132:133]
	s_mov_b32 m0, s40
	s_nop 0
	v_lshl_add_u64 v[202:203], s[34:35], 0, v[130:131]
	s_add_i32 m0, s40, 0x2000
	s_nop 0
	v_lshl_add_u64 v[202:203], v[244:245], 0, s[66:67]
	s_mov_b32 m0, s84
	s_nop 0
	v_lshl_add_u64 v[202:203], v[246:247], 0, s[66:67]
	s_mov_b32 m0, s85
	s_nop 0
	s_waitcnt vmcnt(4)
	s_waitcnt lgkmcnt(0)
	s_barrier
	s_setprio 1
	s_waitcnt lgkmcnt(0)
	v_mfma_f32_16x16x32_bf16 v[62:65], v[156:159], v[212:215], v[62:65]
	v_mfma_f32_16x16x32_bf16 v[58:61], v[164:167], v[212:215], v[58:61]
	v_mfma_f32_16x16x32_bf16 v[46:49], v[156:159], v[220:223], v[46:49]
	v_mfma_f32_16x16x32_bf16 v[42:45], v[164:167], v[220:223], v[42:45]
	v_mfma_f32_16x16x32_bf16 v[30:33], v[156:159], v[228:231], v[30:33]
	v_mfma_f32_16x16x32_bf16 v[26:29], v[164:167], v[228:231], v[26:29]
	v_mfma_f32_16x16x32_bf16 v[14:17], v[156:159], v[236:239], v[14:17]
	v_mfma_f32_16x16x32_bf16 v[10:13], v[164:167], v[236:239], v[10:13]
	v_mfma_f32_16x16x32_bf16 v[62:65], v[160:163], v[216:219], v[62:65]
	v_mfma_f32_16x16x32_bf16 v[58:61], v[168:171], v[216:219], v[58:61]
	v_mfma_f32_16x16x32_bf16 v[46:49], v[160:163], v[224:227], v[46:49]
	v_mfma_f32_16x16x32_bf16 v[42:45], v[168:171], v[224:227], v[42:45]
	v_mfma_f32_16x16x32_bf16 v[30:33], v[160:163], v[232:235], v[30:33]
	v_mfma_f32_16x16x32_bf16 v[26:29], v[168:171], v[232:235], v[26:29]
	v_mfma_f32_16x16x32_bf16 v[14:17], v[160:163], v[240:243], v[14:17]
	v_mfma_f32_16x16x32_bf16 v[10:13], v[168:171], v[240:243], v[10:13]
	s_setprio 0
	s_setprio 1
	s_setprio 0
	s_barrier
	s_add_i32 s62, s62, 2
	s_add_u32 s30, s30, 0x100
	s_addc_u32 s31, s31, 0
	s_add_u32 s52, s52, 0x100
	s_addc_u32 s54, s54, 0
	s_cmp_gt_u32 s62, 13
	s_cbranch_scc0 .Lkuq_2
	s_branch .Lku_exit
; #define PG8_STAGE(bufoff, gbase, voff) do { _Pragma("unroll") for (int _i = 0; _i < 2; ++_i) \
;         __builtin_amdgcn_global_load_lds((const unsigned*)((const char*)(gbase) + (voff)[_i]), (PG8_LAS unsigned*)(lds + (bufoff) + ldsw + _i * 8192), 16, 0, 0); } while (0)
; #define PG8_LDA(dst, b, h) do { _Pragma("unroll") for (int m = 0; m < 4; ++m) _Pragma("unroll") for (int k = 0; k < 2; ++k) dst[m][k] = *(const PG8_LAS bf16x8*)(lds + PG8_SA(b, h) + aoff + m * 2048 + k * 1024); } while (0)
; #define PG8_LDB(dst, b, h) do { _Pragma("unroll") for (int n = 0; n < 2; ++n) _Pragma("unroll") for (int k = 0; k < 2; ++k) dst[n][k] = *(const PG8_LAS bf16x8*)(lds + PG8_SB(b, h) + boff + n * 2048 + k * 1024); } while (0)
; #define PG8_MMA(ai, bj, At, Bt) do { __builtin_amdgcn_s_setprio(1); _Pragma("unroll") for (int m = 0; m < 4; ++m) _Pragma("unroll") for (int n = 0; n < 2; ++n) _Pragma("unroll") for (int k = 0; k < 2; ++k) \
;         acc[ai][bj][m][n] = __builtin_amdgcn_mfma_f32_16x16x32_bf16(Bt[n][k], At[m][k], acc[ai][bj][m][n], 0, 0, 0); __builtin_amdgcn_s_setprio(0); } while (0)
; #define PG8_WAIT_V(n) asm volatile("s_waitcnt vmcnt(" #n ")" ::: "memory")
; template <class Epi, class Sched, bool ALIGN_EPI = false, bool SP2 = false>
; __device__ __forceinline__ void gemm_phase(PG8_LAS unsigned char* lds, const Gemm g, const Sched& S, const Epi& E) {
;     ...
;             PG8_LDB(B0, 0, 0); PG8_LDB(B1, 0, 1); PG8_SCHED; PG8_LDA(At, 0, 0); PG8_STAGE(PG8_SA(1, 1), a1 + hstep, voffA);
;             PG8_WAIT_V(8); PG8_WAIT_L(0); PG8_BAR; PG8_MMA(0, 0, At, B0); PG8_MMA(0, 1, At, B1); PG8_BAR; PG8_SCHED;
;             PG8_LDA(At, 0, 1); PG8_STAGE(PG8_SB(0, 0), b2, voffB); PG8_STAGE(PG8_SB(0, 1), b2 + hstep, voffB); PG8_STAGE(PG8_SA(0, 0), a2, voffA);
;             PG8_WAIT_V(8); PG8_WAIT_L(0); PG8_BAR; PG8_MMA(1, 0, At, B0); PG8_MMA(1, 1, At, B1); PG8_BAR; PG8_SCHED;
;             PG8_LDB(B0, 1, 0); PG8_LDB(B1, 1, 1); PG8_SCHED; PG8_LDA(At, 1, 0); PG8_STAGE(PG8_SA(0, 1), a2 + hstep, voffA);
;             PG8_WAIT_V(8); PG8_WAIT_L(0); PG8_BAR; PG8_MMA(0, 0, At, B0); PG8_MMA(0, 1, At, B1); PG8_BAR; PG8_SCHED;
;             PG8_LDA(At, 1, 1); PG8_STAGE(PG8_SB(1, 0), b3, voffB); PG8_STAGE(PG8_SB(1, 1), b3 + hstep, voffB); PG8_STAGE(PG8_SA(1, 0), a3, voffA);
;             PG8_WAIT_V(8); PG8_WAIT_L(0); PG8_BAR; PG8_MMA(1, 0, At, B0); PG8_MMA(1, 1, At, B1); PG8_BAR; PG8_SCHED;
.Lkuq_3:
	s_add_u32 s34, s30, 0xfffc0080
	s_addc_u32 s35, s31, -1
	s_add_i32 s71, 0, 0x10000
	s_cmp_eq_u32 s62, 12
	s_cselect_b32 s41, s21, s35
	s_cselect_b32 s40, s27, s34
	v_add_u32_e32 v155, s71, v145
	s_cselect_b32 s35, s19, s54
	s_cselect_b32 s34, s50, s52
	s_add_i32 s74, 0, 0x14000
	v_add_u32_e32 v155, s74, v145
	ds_read_b128 v[172:175], v155
	ds_read_b128 v[176:179], v155 offset:1024
	ds_read_b128 v[180:183], v155 offset:2048
	ds_read_b128 v[208:211], v155 offset:3072
	v_lshl_add_u64 v[202:203], s[30:31], 0, v[134:135]
	s_add_i32 m0, s29, 0xc000
	ds_read_b128 v[212:215], v154
	ds_read_b128 v[216:219], v154 offset:1024
	ds_read_b128 v[220:223], v154 offset:2048
	ds_read_b128 v[224:227], v154 offset:3072
	ds_read_b128 v[228:231], v154 offset:4096
	ds_read_b128 v[232:235], v154 offset:5120
	ds_read_b128 v[236:239], v154 offset:6144
	ds_read_b128 v[240:243], v154 offset:7168
	v_lshl_add_u64 v[202:203], s[30:31], 0, v[136:137]
	s_add_i32 m0, s29, 0xe000
	s_nop 0
	s_waitcnt vmcnt(4)
	s_waitcnt lgkmcnt(0)
	s_barrier
	s_setprio 1
	s_waitcnt lgkmcnt(0)
	s_setprio 0
	s_setprio 1
	v_mfma_f32_16x16x32_bf16 v[118:121], v[172:175], v[212:215], v[118:121]
	v_mfma_f32_16x16x32_bf16 v[114:117], v[180:183], v[212:215], v[114:117]
	v_mfma_f32_16x16x32_bf16 v[102:105], v[172:175], v[220:223], v[102:105]
	v_mfma_f32_16x16x32_bf16 v[98:101], v[180:183], v[220:223], v[98:101]
	v_mfma_f32_16x16x32_bf16 v[86:89], v[172:175], v[228:231], v[86:89]
	v_mfma_f32_16x16x32_bf16 v[82:85], v[180:183], v[228:231], v[82:85]
	v_mfma_f32_16x16x32_bf16 v[70:73], v[172:175], v[236:239], v[70:73]
	v_mfma_f32_16x16x32_bf16 v[66:69], v[180:183], v[236:239], v[66:69]
	v_mfma_f32_16x16x32_bf16 v[118:121], v[176:179], v[216:219], v[118:121]
	v_mfma_f32_16x16x32_bf16 v[114:117], v[208:211], v[216:219], v[114:117]
	v_mfma_f32_16x16x32_bf16 v[102:105], v[176:179], v[224:227], v[102:105]
	v_mfma_f32_16x16x32_bf16 v[98:101], v[208:211], v[224:227], v[98:101]
	v_mfma_f32_16x16x32_bf16 v[86:89], v[176:179], v[232:235], v[86:89]
	v_mfma_f32_16x16x32_bf16 v[82:85], v[208:211], v[232:235], v[82:85]
	v_mfma_f32_16x16x32_bf16 v[70:73], v[176:179], v[240:243], v[70:73]
	v_mfma_f32_16x16x32_bf16 v[66:69], v[208:211], v[240:243], v[66:69]
	s_setprio 0
	s_barrier
	s_add_i32 s71, s71, s80
	v_lshl_add_u64 v[202:203], s[34:35], 0, v[132:133]
	s_mov_b32 m0, s71
	s_add_i32 m0, s71, 0x2000
	s_add_u32 s72, s34, 0x40000
	v_lshl_add_u64 v[204:205], s[34:35], 0, v[130:131]
	s_addc_u32 s73, s35, 0
	s_add_i32 s71, s74, s80
	v_lshl_add_u64 v[244:245], s[72:73], 0, v[132:133]
	s_mov_b32 m0, s71
	v_lshl_add_u64 v[246:247], s[40:41], 0, v[130:131]
	global_load_lds_dwordx4 v[244:245], off
	v_lshl_add_u64 v[244:245], s[72:73], 0, v[130:131]
	s_add_i32 m0, s71, 0x2000
	s_nop 0
	global_load_lds_dwordx4 v[244:245], off
	v_lshl_add_u64 v[244:245], s[40:41], 0, v[132:133]
	s_mov_b32 m0, s29
	s_nop 0
	global_load_lds_dwordx4 v[244:245], off
	s_mov_b32 m0, s81
	s_nop 0
	global_load_lds_dwordx4 v[246:247], off
	s_waitcnt vmcnt(4)
	s_waitcnt lgkmcnt(0)
	s_barrier
	s_setprio 1
	s_waitcnt lgkmcnt(0)
	s_setprio 0
	s_setprio 1
	s_setprio 0
	s_barrier
	s_add_i32 s71, 0, 0x18000
	v_add_u32_e32 v155, s71, v145
	s_add_i32 s72, 0, 0x1c000
	v_add_u32_e32 v155, s72, v145
	ds_read_b128 v[172:175], v155
	ds_read_b128 v[176:179], v155 offset:1024
	ds_read_b128 v[180:183], v155 offset:2048
	ds_read_b128 v[208:211], v155 offset:3072
	s_add_u32 s40, s40, 0x40000
	s_addc_u32 s41, s41, 0
	s_mov_b32 m0, s82
	v_lshl_add_u64 v[248:249], s[40:41], 0, v[132:133]
	ds_read_b128 v[212:215], v154 offset:32768
	ds_read_b128 v[216:219], v154 offset:33792
	ds_read_b128 v[220:223], v154 offset:34816
	ds_read_b128 v[224:227], v154 offset:35840
	ds_read_b128 v[228:231], v154 offset:36864
	ds_read_b128 v[232:235], v154 offset:37888
	ds_read_b128 v[236:239], v154 offset:38912
	ds_read_b128 v[240:243], v154 offset:39936
	v_lshl_add_u64 v[248:249], s[40:41], 0, v[130:131]
	s_mov_b32 m0, s83
	s_nop 0
	s_waitcnt vmcnt(4)
	s_waitcnt lgkmcnt(0)
	s_barrier
	s_setprio 1
	s_waitcnt lgkmcnt(0)
	s_setprio 0
	s_setprio 1
	v_mfma_f32_16x16x32_bf16 v[118:121], v[172:175], v[212:215], v[118:121]
	v_mfma_f32_16x16x32_bf16 v[114:117], v[180:183], v[212:215], v[114:117]
	v_mfma_f32_16x16x32_bf16 v[102:105], v[172:175], v[220:223], v[102:105]
	v_mfma_f32_16x16x32_bf16 v[98:101], v[180:183], v[220:223], v[98:101]
	v_mfma_f32_16x16x32_bf16 v[86:89], v[172:175], v[228:231], v[86:89]
	v_mfma_f32_16x16x32_bf16 v[82:85], v[180:183], v[228:231], v[82:85]
	v_mfma_f32_16x16x32_bf16 v[70:73], v[172:175], v[236:239], v[70:73]
	v_mfma_f32_16x16x32_bf16 v[66:69], v[180:183], v[236:239], v[66:69]
	v_mfma_f32_16x16x32_bf16 v[118:121], v[176:179], v[216:219], v[118:121]
	v_mfma_f32_16x16x32_bf16 v[114:117], v[208:211], v[216:219], v[114:117]
	v_mfma_f32_16x16x32_bf16 v[102:105], v[176:179], v[224:227], v[102:105]
	v_mfma_f32_16x16x32_bf16 v[98:101], v[208:211], v[224:227], v[98:101]
	v_mfma_f32_16x16x32_bf16 v[86:89], v[176:179], v[232:235], v[86:89]
	v_mfma_f32_16x16x32_bf16 v[82:85], v[208:211], v[232:235], v[82:85]
	v_mfma_f32_16x16x32_bf16 v[70:73], v[176:179], v[240:243], v[70:73]
	v_mfma_f32_16x16x32_bf16 v[66:69], v[208:211], v[240:243], v[66:69]
	s_setprio 0
	s_barrier
	s_add_i32 s40, s71, s80
	v_lshl_add_u64 v[202:203], v[202:203], 0, s[66:67]
	s_mov_b32 m0, s40
	s_add_i32 m0, s40, 0x2000
	s_add_u32 s34, s34, 0x40080
	v_lshl_add_u64 v[202:203], v[204:205], 0, s[66:67]
	s_addc_u32 s35, s35, 0
	s_add_i32 s40, s72, s80
	v_lshl_add_u64 v[202:203], s[34:35], 0, v[132:133]
	s_mov_b32 m0, s40
	s_nop 0
	global_load_lds_dwordx4 v[202:203], off
	v_lshl_add_u64 v[202:203], s[34:35], 0, v[130:131]
	s_add_i32 m0, s40, 0x2000
	s_nop 0
	global_load_lds_dwordx4 v[202:203], off
	v_lshl_add_u64 v[202:203], v[244:245], 0, s[66:67]
	s_mov_b32 m0, s84
	s_nop 0
	global_load_lds_dwordx4 v[202:203], off
	v_lshl_add_u64 v[202:203], v[246:247], 0, s[66:67]
	s_mov_b32 m0, s85
	s_nop 0
	global_load_lds_dwordx4 v[202:203], off
	s_waitcnt vmcnt(4)
	s_waitcnt lgkmcnt(0)
	s_barrier
	s_setprio 1
	s_waitcnt lgkmcnt(0)
	s_setprio 0
	s_setprio 1
	s_setprio 0
	s_barrier
	s_add_i32 s62, s62, 2
	s_add_u32 s30, s30, 0x100
	s_addc_u32 s31, s31, 0
	s_add_u32 s52, s52, 0x100
	s_addc_u32 s54, s54, 0
	s_cmp_gt_u32 s62, 13
	s_cbranch_scc0 .Lkuq_3
	s_branch .Lku_exit
; #define PG8_STAGE(bufoff, gbase, voff) do { _Pragma("unroll") for (int _i = 0; _i < 2; ++_i) \
;         __builtin_amdgcn_global_load_lds((const unsigned*)((const char*)(gbase) + (voff)[_i]), (PG8_LAS unsigned*)(lds + (bufoff) + ldsw + _i * 8192), 16, 0, 0); } while (0)
; #define PG8_LDA(dst, b, h) do { _Pragma("unroll") for (int m = 0; m < 4; ++m) _Pragma("unroll") for (int k = 0; k < 2; ++k) dst[m][k] = *(const PG8_LAS bf16x8*)(lds + PG8_SA(b, h) + aoff + m * 2048 + k * 1024); } while (0)
; #define PG8_LDB(dst, b, h) do { _Pragma("unroll") for (int n = 0; n < 2; ++n) _Pragma("unroll") for (int k = 0; k < 2; ++k) dst[n][k] = *(const PG8_LAS bf16x8*)(lds + PG8_SB(b, h) + boff + n * 2048 + k * 1024); } while (0)
; #define PG8_MMA(ai, bj, At, Bt) do { __builtin_amdgcn_s_setprio(1); _Pragma("unroll") for (int m = 0; m < 4; ++m) _Pragma("unroll") for (int n = 0; n < 2; ++n) _Pragma("unroll") for (int k = 0; k < 2; ++k) \
;         acc[ai][bj][m][n] = __builtin_amdgcn_mfma_f32_16x16x32_bf16(Bt[n][k], At[m][k], acc[ai][bj][m][n], 0, 0, 0); __builtin_amdgcn_s_setprio(0); } while (0)
; #define PG8_WAIT_V(n) asm volatile("s_waitcnt vmcnt(" #n ")" ::: "memory")
; template <class Epi, class Sched, bool ALIGN_EPI = false, bool SP2 = false>
; __device__ __forceinline__ void gemm_phase(PG8_LAS unsigned char* lds, const Gemm g, const Sched& S, const Epi& E) {
;     ...
;             PG8_LDB(B0, 0, 0); PG8_LDB(B1, 0, 1); PG8_SCHED; PG8_LDA(At, 0, 0); PG8_STAGE(PG8_SA(1, 1), a1 + hstep, voffA);
;             PG8_WAIT_V(8); PG8_WAIT_L(0); PG8_BAR; PG8_MMA(0, 0, At, B0); PG8_MMA(0, 1, At, B1); PG8_BAR; PG8_SCHED;
;             PG8_LDA(At, 0, 1); PG8_STAGE(PG8_SB(0, 0), b2, voffB); PG8_STAGE(PG8_SB(0, 1), b2 + hstep, voffB); PG8_STAGE(PG8_SA(0, 0), a2, voffA);
;             PG8_WAIT_V(8); PG8_WAIT_L(0); PG8_BAR; PG8_MMA(1, 0, At, B0); PG8_MMA(1, 1, At, B1); PG8_BAR; PG8_SCHED;
;             PG8_LDB(B0, 1, 0); PG8_LDB(B1, 1, 1); PG8_SCHED; PG8_LDA(At, 1, 0); PG8_STAGE(PG8_SA(0, 1), a2 + hstep, voffA);
;             PG8_WAIT_V(8); PG8_WAIT_L(0); PG8_BAR; PG8_MMA(0, 0, At, B0); PG8_MMA(0, 1, At, B1); PG8_BAR; PG8_SCHED;
;             PG8_LDA(At, 1, 1); PG8_STAGE(PG8_SB(1, 0), b3, voffB); PG8_STAGE(PG8_SB(1, 1), b3 + hstep, voffB); PG8_STAGE(PG8_SA(1, 0), a3, voffA);
;             PG8_WAIT_V(8); PG8_WAIT_L(0); PG8_BAR; PG8_MMA(1, 0, At, B0); PG8_MMA(1, 1, At, B1); PG8_BAR; PG8_SCHED;
.Lkuq_4:
	s_add_u32 s34, s30, 0xfffc0080
	s_addc_u32 s35, s31, -1
	s_add_i32 s71, 0, 0x10000
	s_cmp_eq_u32 s62, 12
	s_cselect_b32 s41, s21, s35
	s_cselect_b32 s40, s27, s34
	v_add_u32_e32 v155, s71, v145
	s_cselect_b32 s35, s19, s54
	s_cselect_b32 s34, s50, s52
	s_add_i32 s74, 0, 0x14000
	v_add_u32_e32 v155, s74, v145
	ds_read_b128 v[172:175], v155
	ds_read_b128 v[176:179], v155 offset:1024
	ds_read_b128 v[180:183], v155 offset:2048
	ds_read_b128 v[208:211], v155 offset:3072
	v_lshl_add_u64 v[202:203], s[30:31], 0, v[134:135]
	s_add_i32 m0, s29, 0xc000
	global_load_lds_dwordx4 v[202:203], off
	v_lshl_add_u64 v[202:203], s[30:31], 0, v[136:137]
	s_add_i32 m0, s29, 0xe000
	s_nop 0
	global_load_lds_dwordx4 v[202:203], off
	s_waitcnt vmcnt(4)
	s_waitcnt lgkmcnt(0)
	s_barrier
	s_setprio 1
	s_waitcnt lgkmcnt(0)
	s_setprio 0
	s_setprio 1
	s_setprio 0
	s_barrier
	s_add_i32 s71, s71, s80
	v_lshl_add_u64 v[202:203], s[34:35], 0, v[132:133]
	s_mov_b32 m0, s71
	ds_read_b128 v[212:215], v154 offset:16384
	ds_read_b128 v[216:219], v154 offset:17408
	ds_read_b128 v[220:223], v154 offset:18432
	ds_read_b128 v[224:227], v154 offset:19456
	ds_read_b128 v[228:231], v154 offset:20480
	ds_read_b128 v[232:235], v154 offset:21504
	ds_read_b128 v[236:239], v154 offset:22528
	ds_read_b128 v[240:243], v154 offset:23552
	s_add_i32 m0, s71, 0x2000
	s_add_u32 s72, s34, 0x40000
	v_lshl_add_u64 v[204:205], s[34:35], 0, v[130:131]
	s_addc_u32 s73, s35, 0
	s_add_i32 s71, s74, s80
	v_lshl_add_u64 v[244:245], s[72:73], 0, v[132:133]
	s_mov_b32 m0, s71
	v_lshl_add_u64 v[246:247], s[40:41], 0, v[130:131]
	global_load_lds_dwordx4 v[244:245], off
	v_lshl_add_u64 v[244:245], s[72:73], 0, v[130:131]
	s_add_i32 m0, s71, 0x2000
	s_nop 0
	global_load_lds_dwordx4 v[244:245], off
	v_lshl_add_u64 v[244:245], s[40:41], 0, v[132:133]
	s_mov_b32 m0, s29
	s_nop 0
	s_mov_b32 m0, s81
	s_nop 0
	s_waitcnt vmcnt(4)
	s_waitcnt lgkmcnt(0)
	s_barrier
	s_setprio 1
	s_waitcnt lgkmcnt(0)
	s_setprio 0
	s_setprio 1
	v_mfma_f32_16x16x32_bf16 v[54:57], v[172:175], v[212:215], v[54:57]
	v_mfma_f32_16x16x32_bf16 v[50:53], v[180:183], v[212:215], v[50:53]
	v_mfma_f32_16x16x32_bf16 v[38:41], v[172:175], v[220:223], v[38:41]
	v_mfma_f32_16x16x32_bf16 v[34:37], v[180:183], v[220:223], v[34:37]
	v_mfma_f32_16x16x32_bf16 v[22:25], v[172:175], v[228:231], v[22:25]
	v_mfma_f32_16x16x32_bf16 v[18:21], v[180:183], v[228:231], v[18:21]
	v_mfma_f32_16x16x32_bf16 v[6:9], v[172:175], v[236:239], v[6:9]
	v_mfma_f32_16x16x32_bf16 v[2:5], v[180:183], v[236:239], v[2:5]
	v_mfma_f32_16x16x32_bf16 v[54:57], v[176:179], v[216:219], v[54:57]
	v_mfma_f32_16x16x32_bf16 v[50:53], v[208:211], v[216:219], v[50:53]
	v_mfma_f32_16x16x32_bf16 v[38:41], v[176:179], v[224:227], v[38:41]
	v_mfma_f32_16x16x32_bf16 v[34:37], v[208:211], v[224:227], v[34:37]
	v_mfma_f32_16x16x32_bf16 v[22:25], v[176:179], v[232:235], v[22:25]
	v_mfma_f32_16x16x32_bf16 v[18:21], v[208:211], v[232:235], v[18:21]
	v_mfma_f32_16x16x32_bf16 v[6:9], v[176:179], v[240:243], v[6:9]
	v_mfma_f32_16x16x32_bf16 v[2:5], v[208:211], v[240:243], v[2:5]
	s_setprio 0
	s_barrier
	s_add_i32 s71, 0, 0x18000
	v_add_u32_e32 v155, s71, v145
	s_add_i32 s72, 0, 0x1c000
	v_add_u32_e32 v155, s72, v145
	ds_read_b128 v[172:175], v155
	ds_read_b128 v[176:179], v155 offset:1024
	ds_read_b128 v[180:183], v155 offset:2048
	ds_read_b128 v[208:211], v155 offset:3072
	s_add_u32 s40, s40, 0x40000
	s_addc_u32 s41, s41, 0
	s_mov_b32 m0, s82
	v_lshl_add_u64 v[248:249], s[40:41], 0, v[132:133]
	global_load_lds_dwordx4 v[248:249], off
	v_lshl_add_u64 v[248:249], s[40:41], 0, v[130:131]
	s_mov_b32 m0, s83
	s_nop 0
	global_load_lds_dwordx4 v[248:249], off
	s_waitcnt vmcnt(4)
	s_waitcnt lgkmcnt(0)
	s_barrier
	s_setprio 1
	s_waitcnt lgkmcnt(0)
	s_setprio 0
	s_setprio 1
	s_setprio 0
	s_barrier
	s_add_i32 s40, s71, s80
	v_lshl_add_u64 v[202:203], v[202:203], 0, s[66:67]
	s_mov_b32 m0, s40
	ds_read_b128 v[212:215], v154 offset:49152
	ds_read_b128 v[216:219], v154 offset:50176
	ds_read_b128 v[220:223], v154 offset:51200
	ds_read_b128 v[224:227], v154 offset:52224
	ds_read_b128 v[228:231], v154 offset:53248
	ds_read_b128 v[232:235], v154 offset:54272
	ds_read_b128 v[236:239], v154 offset:55296
	ds_read_b128 v[240:243], v154 offset:56320
	s_add_i32 m0, s40, 0x2000
	s_add_u32 s34, s34, 0x40080
	v_lshl_add_u64 v[202:203], v[204:205], 0, s[66:67]
	s_addc_u32 s35, s35, 0
	s_add_i32 s40, s72, s80
	v_lshl_add_u64 v[202:203], s[34:35], 0, v[132:133]
	s_mov_b32 m0, s40
	s_nop 0
	global_load_lds_dwordx4 v[202:203], off
	v_lshl_add_u64 v[202:203], s[34:35], 0, v[130:131]
	s_add_i32 m0, s40, 0x2000
	s_nop 0
	global_load_lds_dwordx4 v[202:203], off
	v_lshl_add_u64 v[202:203], v[244:245], 0, s[66:67]
	s_mov_b32 m0, s84
	s_nop 0
	v_lshl_add_u64 v[202:203], v[246:247], 0, s[66:67]
	s_mov_b32 m0, s85
	s_nop 0
	s_waitcnt vmcnt(4)
	s_waitcnt lgkmcnt(0)
	s_barrier
	s_setprio 1
	s_waitcnt lgkmcnt(0)
	s_setprio 0
	s_setprio 1
	v_mfma_f32_16x16x32_bf16 v[54:57], v[172:175], v[212:215], v[54:57]
	v_mfma_f32_16x16x32_bf16 v[50:53], v[180:183], v[212:215], v[50:53]
	v_mfma_f32_16x16x32_bf16 v[38:41], v[172:175], v[220:223], v[38:41]
	v_mfma_f32_16x16x32_bf16 v[34:37], v[180:183], v[220:223], v[34:37]
	v_mfma_f32_16x16x32_bf16 v[22:25], v[172:175], v[228:231], v[22:25]
	v_mfma_f32_16x16x32_bf16 v[18:21], v[180:183], v[228:231], v[18:21]
	v_mfma_f32_16x16x32_bf16 v[6:9], v[172:175], v[236:239], v[6:9]
	v_mfma_f32_16x16x32_bf16 v[2:5], v[180:183], v[236:239], v[2:5]
	v_mfma_f32_16x16x32_bf16 v[54:57], v[176:179], v[216:219], v[54:57]
	v_mfma_f32_16x16x32_bf16 v[50:53], v[208:211], v[216:219], v[50:53]
	v_mfma_f32_16x16x32_bf16 v[38:41], v[176:179], v[224:227], v[38:41]
	v_mfma_f32_16x16x32_bf16 v[34:37], v[208:211], v[224:227], v[34:37]
	v_mfma_f32_16x16x32_bf16 v[22:25], v[176:179], v[232:235], v[22:25]
	v_mfma_f32_16x16x32_bf16 v[18:21], v[208:211], v[232:235], v[18:21]
	v_mfma_f32_16x16x32_bf16 v[6:9], v[176:179], v[240:243], v[6:9]
	v_mfma_f32_16x16x32_bf16 v[2:5], v[208:211], v[240:243], v[2:5]
	s_setprio 0
	s_barrier
	s_add_i32 s62, s62, 2
	s_add_u32 s30, s30, 0x100
	s_addc_u32 s31, s31, 0
	s_add_u32 s52, s52, 0x100
	s_addc_u32 s54, s54, 0
	s_cmp_gt_u32 s62, 13
	s_cbranch_scc0 .Lkuq_4

; __device__ __forceinline__ unsigned pk2(float lo, float hi) { unsigned r; asm("v_cvt_pk_bf16_f32 %0, %1, %2" : "=v"(r) : "v"(lo), "v"(hi)); return r; }
; __device__ __forceinline__ float siluf(float v) { return v * __builtin_amdgcn_rcpf(1.f + __expf(-v)); }
;     __device__ __forceinline__ void operator()(const f32x4 (&acc)[2][2][4][2], const Unit& u, int wr, int wc, int fr, int fq) const {
; #pragma unroll
;         for (int ai = 0; ai < 2; ++ai)
; #pragma unroll
;             for (int m = 0; m < 4; ++m) {
;                 const int row = u.pm * 256 + ai * 128 + wr * 64 + m * 16 + fr;
;                 const f32x4 g0 = acc[ai][0][m][0], u0 = acc[ai][0][m][1], g1 = acc[ai][1][m][0], u1 = acc[ai][1][m][1];
;                 u32x4 w;
;                 w.x = pk2(siluf(g0[0]) * u0[0], siluf(g0[1]) * u0[1]); w.y = pk2(siluf(g0[2]) * u0[2], siluf(g0[3]) * u0[3]);
;                 w.z = pk2(siluf(g1[0]) * u1[0], siluf(g1[1]) * u1[1]); w.w = pk2(siluf(g1[2]) * u1[2], siluf(g1[3]) * u1[3]);
;                 *(u32x4*)(act + (size_t)row * DFF + u.pn * 128 + wc * 32 + 8 * fq) = w;
;             }
.LBB0_166:
	s_and_b32 s98, s101, 7
	s_cmp_lg_u32 s98, 0
	s_cbranch_scc0 .Lkuq_epi_full
	s_and_b32 s98, s101, 7
	s_cmp_eq_u32 s98, 1
	s_cbranch_scc1 .Lkuq_epi1
	s_and_b32 s98, s101, 7
	s_cmp_eq_u32 s98, 2
	s_cbranch_scc1 .Lkuq_epi2
	s_and_b32 s98, s101, 7
	s_cmp_eq_u32 s98, 3
	s_cbranch_scc1 .Lkuq_epi3
	s_and_b32 s98, s101, 7
	s_cmp_eq_u32 s98, 4
	s_cbranch_scc1 .Lkuq_epi4
	s_and_b32 s98, s101, 7
	s_cmp_eq_u32 s98, 6
	s_cbranch_scc1 .Lku_epi_skip0
.Lkuq_epi_full:
	v_mul_f32_e32 v156, 0xbfb8aa3b, v126
	v_exp_f32_e32 v156, v156
	s_lshl_b32 s19, s28, 8
	s_lshl_b32 s26, s26, 7
	v_add_u32_e32 v155, s19, v143
	v_add_f32_e32 v156, 1.0, v156
	v_rcp_f32_e32 v156, v156
	s_movk_i32 s21, 0x1600
	s_ashr_i32 s27, s26, 31
	s_lshl_b64 s[26:27], s[26:27], 1
	v_mul_f32_e32 v126, v126, v156
	v_mul_f32_e32 v122, v122, v126
	v_mul_f32_e32 v126, 0xbfb8aa3b, v127
	v_exp_f32_e32 v126, v126
	s_andn2_b64 vcc, exec, s[6:7]
	v_add_f32_e32 v126, 1.0, v126
	v_rcp_f32_e32 v126, v126
	s_nop 0
	v_mul_f32_e32 v126, v127, v126
	v_mul_f32_e32 v123, v123, v126
	v_cvt_pk_bf16_f32 v122, v122, v123
	v_mul_f32_e32 v123, 0xbfb8aa3b, v128
	v_exp_f32_e32 v123, v123
	s_nop 0
	v_add_f32_e32 v123, 1.0, v123
	v_rcp_f32_e32 v123, v123
	s_nop 0
	v_mul_f32_e32 v123, v128, v123
	v_mul_f32_e32 v123, v124, v123
	v_mul_f32_e32 v124, 0xbfb8aa3b, v129
	v_exp_f32_e32 v124, v124
	s_nop 0
	v_add_f32_e32 v124, 1.0, v124
	v_rcp_f32_e32 v124, v124
	s_nop 0
	v_mul_f32_e32 v124, v129, v124
	v_mul_f32_e32 v124, v125, v124
	v_cvt_pk_bf16_f32 v123, v123, v124
	v_mul_f32_e32 v124, 0xbfb8aa3b, v118
	v_exp_f32_e32 v124, v124
	s_nop 0
	v_add_f32_e32 v124, 1.0, v124
	v_rcp_f32_e32 v124, v124
	s_nop 0
	v_mul_f32_e32 v118, v118, v124
	v_mul_f32_e32 v114, v114, v118
	v_mul_f32_e32 v118, 0xbfb8aa3b, v119
	v_exp_f32_e32 v118, v118
	s_nop 0
	v_add_f32_e32 v118, 1.0, v118
	v_rcp_f32_e32 v118, v118
	s_nop 0
	v_mul_f32_e32 v118, v119, v118
	v_mul_f32_e32 v115, v115, v118
	v_cvt_pk_bf16_f32 v124, v114, v115
	v_mul_f32_e32 v114, 0xbfb8aa3b, v120
	v_mul_f32_e32 v115, 0xbfb8aa3b, v121
	v_exp_f32_e32 v114, v114
	v_exp_f32_e32 v115, v115
	v_add_f32_e32 v114, 1.0, v114
	v_add_f32_e32 v115, 1.0, v115
	v_rcp_f32_e32 v114, v114
	v_rcp_f32_e32 v115, v115
	v_mul_f32_e32 v114, v120, v114
	v_mul_f32_e32 v115, v121, v115
	v_mul_f32_e32 v114, v116, v114
	v_mul_f32_e32 v115, v117, v115
	v_cvt_pk_bf16_f32 v125, v114, v115
	v_mov_b64_e32 v[114:115], s[14:15]
	v_mad_i64_i32 v[116:117], s[30:31], v155, s21, v[114:115]
	v_lshl_add_u64 v[116:117], v[116:117], 0, s[26:27]
	v_lshl_add_u64 v[116:117], v[116:117], 0, s[64:65]
	v_lshl_add_u64 v[116:117], v[116:117], 0, v[0:1]
	global_store_dwordx4 v[116:117], v[122:125], off
	v_mul_f32_e32 v117, 0xbfb8aa3b, v110
	v_exp_f32_e32 v117, v117
	v_add_u32_e32 v116, s19, v147
	v_add_f32_e32 v117, 1.0, v117
	v_rcp_f32_e32 v117, v117
	s_nop 0
	v_mul_f32_e32 v110, v110, v117
	v_mul_f32_e32 v106, v106, v110
	v_mul_f32_e32 v110, 0xbfb8aa3b, v111
	v_exp_f32_e32 v110, v110
	s_nop 0
	v_add_f32_e32 v110, 1.0, v110
	v_rcp_f32_e32 v110, v110
	s_nop 0
	v_mul_f32_e32 v110, v111, v110
	v_mul_f32_e32 v107, v107, v110
	v_cvt_pk_bf16_f32 v106, v106, v107
	v_mul_f32_e32 v107, 0xbfb8aa3b, v112
	v_exp_f32_e32 v107, v107
	s_nop 0
	v_add_f32_e32 v107, 1.0, v107
	v_rcp_f32_e32 v107, v107
	s_nop 0
	v_mul_f32_e32 v107, v112, v107
	v_mul_f32_e32 v107, v108, v107
	v_mul_f32_e32 v108, 0xbfb8aa3b, v113
	v_exp_f32_e32 v108, v108
	s_nop 0
	v_add_f32_e32 v108, 1.0, v108
	v_rcp_f32_e32 v108, v108
	s_nop 0
	v_mul_f32_e32 v108, v113, v108
	v_mul_f32_e32 v108, v109, v108
	v_cvt_pk_bf16_f32 v107, v107, v108
	v_mul_f32_e32 v108, 0xbfb8aa3b, v102
	v_exp_f32_e32 v108, v108
	s_nop 0
	v_add_f32_e32 v108, 1.0, v108
	v_rcp_f32_e32 v108, v108
	s_nop 0
	v_mul_f32_e32 v102, v102, v108
	v_mul_f32_e32 v98, v98, v102
	v_mul_f32_e32 v102, 0xbfb8aa3b, v103
	v_exp_f32_e32 v102, v102
	s_nop 0
	v_add_f32_e32 v102, 1.0, v102
	v_rcp_f32_e32 v102, v102
	s_nop 0
	v_mul_f32_e32 v102, v103, v102
	v_mul_f32_e32 v99, v99, v102
	v_cvt_pk_bf16_f32 v108, v98, v99
	v_mul_f32_e32 v98, 0xbfb8aa3b, v104
	v_mul_f32_e32 v99, 0xbfb8aa3b, v105
	v_exp_f32_e32 v98, v98
	v_exp_f32_e32 v99, v99
	v_add_f32_e32 v98, 1.0, v98
	v_add_f32_e32 v99, 1.0, v99
	v_rcp_f32_e32 v98, v98
	v_rcp_f32_e32 v99, v99
; __device__ __forceinline__ unsigned pk2(float lo, float hi) { unsigned r; asm("v_cvt_pk_bf16_f32 %0, %1, %2" : "=v"(r) : "v"(lo), "v"(hi)); return r; }
; __device__ __forceinline__ float siluf(float v) { return v * __builtin_amdgcn_rcpf(1.f + __expf(-v)); }
;     __device__ __forceinline__ void operator()(const f32x4 (&acc)[2][2][4][2], const Unit& u, int wr, int wc, int fr, int fq) const {
; #pragma unroll
;         for (int ai = 0; ai < 2; ++ai)
; #pragma unroll
;             for (int m = 0; m < 4; ++m) {
;                 const int row = u.pm * 256 + ai * 128 + wr * 64 + m * 16 + fr;
;                 const f32x4 g0 = acc[ai][0][m][0], u0 = acc[ai][0][m][1], g1 = acc[ai][1][m][0], u1 = acc[ai][1][m][1];
;                 u32x4 w;
;                 w.x = pk2(siluf(g0[0]) * u0[0], siluf(g0[1]) * u0[1]); w.y = pk2(siluf(g0[2]) * u0[2], siluf(g0[3]) * u0[3]);
;                 w.z = pk2(siluf(g1[0]) * u1[0], siluf(g1[1]) * u1[1]); w.w = pk2(siluf(g1[2]) * u1[2], siluf(g1[3]) * u1[3]);
;                 *(u32x4*)(act + (size_t)row * DFF + u.pn * 128 + wc * 32 + 8 * fq) = w;
;             }
	v_mul_f32_e32 v98, v104, v98
	v_mul_f32_e32 v99, v105, v99
	v_mul_f32_e32 v98, v100, v98
	v_mul_f32_e32 v99, v101, v99
	v_cvt_pk_bf16_f32 v109, v98, v99
	v_mad_i64_i32 v[98:99], s[30:31], v116, s21, v[114:115]
	v_lshl_add_u64 v[98:99], v[98:99], 0, s[26:27]
	v_lshl_add_u64 v[98:99], v[98:99], 0, s[64:65]
	v_lshl_add_u64 v[98:99], v[98:99], 0, v[0:1]
	global_store_dwordx4 v[98:99], v[106:109], off
	v_mul_f32_e32 v99, 0xbfb8aa3b, v94
	v_exp_f32_e32 v99, v99
	v_add_u32_e32 v98, s19, v148
	v_add_f32_e32 v99, 1.0, v99
	v_rcp_f32_e32 v99, v99
	s_nop 0
	v_mul_f32_e32 v94, v94, v99
	v_mul_f32_e32 v90, v90, v94
	v_mul_f32_e32 v94, 0xbfb8aa3b, v95
	v_exp_f32_e32 v94, v94
	s_nop 0
	v_add_f32_e32 v94, 1.0, v94
	v_rcp_f32_e32 v94, v94
	s_nop 0
	v_mul_f32_e32 v94, v95, v94
	v_mul_f32_e32 v91, v91, v94
	v_cvt_pk_bf16_f32 v90, v90, v91
	v_mul_f32_e32 v91, 0xbfb8aa3b, v96
	v_exp_f32_e32 v91, v91
	s_nop 0
	v_add_f32_e32 v91, 1.0, v91
	v_rcp_f32_e32 v91, v91
	s_nop 0
	v_mul_f32_e32 v91, v96, v91
	v_mul_f32_e32 v91, v92, v91
	v_mul_f32_e32 v92, 0xbfb8aa3b, v97
	v_exp_f32_e32 v92, v92
	s_nop 0
	v_add_f32_e32 v92, 1.0, v92
	v_rcp_f32_e32 v92, v92
	s_nop 0
	v_mul_f32_e32 v92, v97, v92
	v_mul_f32_e32 v92, v93, v92
	v_cvt_pk_bf16_f32 v91, v91, v92
	v_mul_f32_e32 v92, 0xbfb8aa3b, v86
	v_exp_f32_e32 v92, v92
	s_nop 0
	v_add_f32_e32 v92, 1.0, v92
	v_rcp_f32_e32 v92, v92
	s_nop 0
	v_mul_f32_e32 v86, v86, v92
	v_mul_f32_e32 v82, v82, v86
	v_mul_f32_e32 v86, 0xbfb8aa3b, v87
	v_exp_f32_e32 v86, v86
	s_nop 0
	v_add_f32_e32 v86, 1.0, v86
	v_rcp_f32_e32 v86, v86
	s_nop 0
	v_mul_f32_e32 v86, v87, v86
	v_mul_f32_e32 v83, v83, v86
	v_cvt_pk_bf16_f32 v92, v82, v83
	v_mul_f32_e32 v82, 0xbfb8aa3b, v88
	v_mul_f32_e32 v83, 0xbfb8aa3b, v89
	v_exp_f32_e32 v82, v82
	v_exp_f32_e32 v83, v83
	v_add_f32_e32 v82, 1.0, v82
	v_add_f32_e32 v83, 1.0, v83
	v_rcp_f32_e32 v82, v82
	v_rcp_f32_e32 v83, v83
	v_mul_f32_e32 v82, v88, v82
	v_mul_f32_e32 v83, v89, v83
	v_mul_f32_e32 v82, v84, v82
	v_mul_f32_e32 v83, v85, v83
	v_cvt_pk_bf16_f32 v93, v82, v83
	v_mad_i64_i32 v[82:83], s[30:31], v98, s21, v[114:115]
	v_lshl_add_u64 v[82:83], v[82:83], 0, s[26:27]
	v_lshl_add_u64 v[82:83], v[82:83], 0, s[64:65]
	v_lshl_add_u64 v[82:83], v[82:83], 0, v[0:1]
	global_store_dwordx4 v[82:83], v[90:93], off
	v_mul_f32_e32 v83, 0xbfb8aa3b, v78
	v_exp_f32_e32 v83, v83
	v_add_u32_e32 v82, s19, v149
	v_add_f32_e32 v83, 1.0, v83
	v_rcp_f32_e32 v83, v83
	s_nop 0
	v_mul_f32_e32 v78, v78, v83
	v_mul_f32_e32 v74, v74, v78
	v_mul_f32_e32 v78, 0xbfb8aa3b, v79
	v_exp_f32_e32 v78, v78
	s_nop 0
	v_add_f32_e32 v78, 1.0, v78
	v_rcp_f32_e32 v78, v78
	s_nop 0
	v_mul_f32_e32 v78, v79, v78
	v_mul_f32_e32 v75, v75, v78
	v_cvt_pk_bf16_f32 v74, v74, v75
	v_mul_f32_e32 v75, 0xbfb8aa3b, v80
	v_exp_f32_e32 v75, v75
	s_nop 0
	v_add_f32_e32 v75, 1.0, v75
	v_rcp_f32_e32 v75, v75
	s_nop 0
	v_mul_f32_e32 v75, v80, v75
	v_mul_f32_e32 v75, v76, v75
	v_mul_f32_e32 v76, 0xbfb8aa3b, v81
	v_exp_f32_e32 v76, v76
	s_nop 0
	v_add_f32_e32 v76, 1.0, v76
	v_rcp_f32_e32 v76, v76
	s_nop 0
	v_mul_f32_e32 v76, v81, v76
	v_mul_f32_e32 v76, v77, v76
	v_cvt_pk_bf16_f32 v75, v75, v76
	v_mul_f32_e32 v76, 0xbfb8aa3b, v70
	v_exp_f32_e32 v76, v76
	s_nop 0
	v_add_f32_e32 v76, 1.0, v76
	v_rcp_f32_e32 v76, v76
	s_nop 0
	v_mul_f32_e32 v70, v70, v76
	v_mul_f32_e32 v66, v66, v70
	v_mul_f32_e32 v70, 0xbfb8aa3b, v71
	v_exp_f32_e32 v70, v70
	s_nop 0
	v_add_f32_e32 v70, 1.0, v70
	v_rcp_f32_e32 v70, v70
	s_nop 0
	v_mul_f32_e32 v70, v71, v70
	v_mul_f32_e32 v67, v67, v70
	v_cvt_pk_bf16_f32 v76, v66, v67
	v_mul_f32_e32 v66, 0xbfb8aa3b, v72
	v_mul_f32_e32 v67, 0xbfb8aa3b, v73
	v_exp_f32_e32 v66, v66
	v_exp_f32_e32 v67, v67
	v_add_f32_e32 v66, 1.0, v66
	v_add_f32_e32 v67, 1.0, v67
	v_rcp_f32_e32 v66, v66
	v_rcp_f32_e32 v67, v67
	v_mul_f32_e32 v66, v72, v66
	v_mul_f32_e32 v67, v73, v67
	v_mul_f32_e32 v66, v68, v66
	v_mul_f32_e32 v67, v69, v67
	v_cvt_pk_bf16_f32 v77, v66, v67
	v_mad_i64_i32 v[66:67], s[30:31], v82, s21, v[114:115]
	v_lshl_add_u64 v[66:67], v[66:67], 0, s[26:27]
	v_lshl_add_u64 v[66:67], v[66:67], 0, s[64:65]
	v_lshl_add_u64 v[66:67], v[66:67], 0, v[0:1]
	global_store_dwordx4 v[66:67], v[74:77], off
	s_and_b32 s98, s101, 7
	s_cmp_eq_u32 s98, 5
	s_cbranch_scc1 .Lku_epi_skip1
	s_branch .Lku_epi_g4

; __device__ __forceinline__ unsigned pk2(float lo, float hi) { unsigned r; asm("v_cvt_pk_bf16_f32 %0, %1, %2" : "=v"(r) : "v"(lo), "v"(hi)); return r; }
; __device__ __forceinline__ float siluf(float v) { return v * __builtin_amdgcn_rcpf(1.f + __expf(-v)); }
;     __device__ __forceinline__ void operator()(const f32x4 (&acc)[2][2][4][2], const Unit& u, int wr, int wc, int fr, int fq) const {
; #pragma unroll
;         for (int ai = 0; ai < 2; ++ai)
; #pragma unroll
;             for (int m = 0; m < 4; ++m) {
;                 const int row = u.pm * 256 + ai * 128 + wr * 64 + m * 16 + fr;
;                 const f32x4 g0 = acc[ai][0][m][0], u0 = acc[ai][0][m][1], g1 = acc[ai][1][m][0], u1 = acc[ai][1][m][1];
;                 u32x4 w;
;                 w.x = pk2(siluf(g0[0]) * u0[0], siluf(g0[1]) * u0[1]); w.y = pk2(siluf(g0[2]) * u0[2], siluf(g0[3]) * u0[3]);
;                 w.z = pk2(siluf(g1[0]) * u1[0], siluf(g1[1]) * u1[1]); w.w = pk2(siluf(g1[2]) * u1[2], siluf(g1[3]) * u1[3]);
;                 *(u32x4*)(act + (size_t)row * DFF + u.pn * 128 + wc * 32 + 8 * fq) = w;
;             }
.Lku_epi_skip1:
	s_mov_b64 s[26:27], -1
	s_branch .Lku_epi_end
.Lkuq_epi1:
	v_mul_f32_e32 v156, 0xbfb8aa3b, v126
	v_exp_f32_e32 v156, v156
	s_lshl_b32 s19, s28, 8
	s_lshl_b32 s26, s26, 7
	v_add_u32_e32 v155, s19, v143
	v_add_f32_e32 v156, 1.0, v156
	v_rcp_f32_e32 v156, v156
	s_movk_i32 s21, 0x1600
	s_ashr_i32 s27, s26, 31
	s_lshl_b64 s[26:27], s[26:27], 1
	v_mul_f32_e32 v126, v126, v156
	v_mul_f32_e32 v122, v122, v126
	v_mul_f32_e32 v126, 0xbfb8aa3b, v127
	v_exp_f32_e32 v126, v126
	s_andn2_b64 vcc, exec, s[6:7]
	v_add_f32_e32 v126, 1.0, v126
	v_rcp_f32_e32 v126, v126
	s_nop 0
	v_mul_f32_e32 v126, v127, v126
	v_mul_f32_e32 v123, v123, v126
	v_cvt_pk_bf16_f32 v122, v122, v123
	v_mul_f32_e32 v123, 0xbfb8aa3b, v128
	v_exp_f32_e32 v123, v123
	s_nop 0
	v_add_f32_e32 v123, 1.0, v123
	v_rcp_f32_e32 v123, v123
	s_nop 0
	v_mul_f32_e32 v123, v128, v123
	v_mul_f32_e32 v123, v124, v123
	v_mul_f32_e32 v124, 0xbfb8aa3b, v129
	v_exp_f32_e32 v124, v124
	s_nop 0
	v_add_f32_e32 v124, 1.0, v124
	v_rcp_f32_e32 v124, v124
	s_nop 0
	v_mul_f32_e32 v124, v129, v124
	v_mul_f32_e32 v124, v125, v124
	v_cvt_pk_bf16_f32 v123, v123, v124
	s_nop 1
	s_nop 0
	s_nop 1
	s_nop 0
	s_nop 1
	s_nop 0
	s_nop 1
	s_nop 0
	s_nop 1
	s_nop 1
	s_nop 1
	s_nop 1
	v_mov_b64_e32 v[114:115], s[14:15]
	v_mad_i64_i32 v[116:117], s[30:31], v155, s21, v[114:115]
	v_lshl_add_u64 v[116:117], v[116:117], 0, s[26:27]
	v_lshl_add_u64 v[116:117], v[116:117], 0, s[64:65]
	v_lshl_add_u64 v[116:117], v[116:117], 0, v[0:1]
	global_store_dwordx2 v[116:117], v[122:123], off
	s_nop 1
	v_mul_f32_e32 v117, 0xbfb8aa3b, v110
	v_exp_f32_e32 v117, v117
	v_add_u32_e32 v116, s19, v147
	v_add_f32_e32 v117, 1.0, v117
	v_rcp_f32_e32 v117, v117
	s_nop 0
	v_mul_f32_e32 v110, v110, v117
	v_mul_f32_e32 v106, v106, v110
	v_mul_f32_e32 v110, 0xbfb8aa3b, v111
	v_exp_f32_e32 v110, v110
	s_nop 0
	v_add_f32_e32 v110, 1.0, v110
	v_rcp_f32_e32 v110, v110
	s_nop 0
	v_mul_f32_e32 v110, v111, v110
	v_mul_f32_e32 v107, v107, v110
	v_cvt_pk_bf16_f32 v106, v106, v107
	v_mul_f32_e32 v107, 0xbfb8aa3b, v112
	v_exp_f32_e32 v107, v107
	s_nop 0
	v_add_f32_e32 v107, 1.0, v107
	v_rcp_f32_e32 v107, v107
	s_nop 0
	v_mul_f32_e32 v107, v112, v107
	v_mul_f32_e32 v107, v108, v107
	v_mul_f32_e32 v108, 0xbfb8aa3b, v113
	v_exp_f32_e32 v108, v108
	s_nop 0
	v_add_f32_e32 v108, 1.0, v108
	v_rcp_f32_e32 v108, v108
	s_nop 0
	v_mul_f32_e32 v108, v113, v108
	v_mul_f32_e32 v108, v109, v108
	v_cvt_pk_bf16_f32 v107, v107, v108
	s_nop 1
	s_nop 0
	s_nop 1
	s_nop 0
	s_nop 1
	s_nop 0
	s_nop 1
	s_nop 0
	s_nop 1
	s_nop 1
	s_nop 1
	s_nop 1
	v_mad_i64_i32 v[98:99], s[30:31], v116, s21, v[114:115]
	v_lshl_add_u64 v[98:99], v[98:99], 0, s[26:27]
	v_lshl_add_u64 v[98:99], v[98:99], 0, s[64:65]
	v_lshl_add_u64 v[98:99], v[98:99], 0, v[0:1]
	global_store_dwordx2 v[98:99], v[106:107], off
	s_nop 1
	v_mul_f32_e32 v99, 0xbfb8aa3b, v94
	v_exp_f32_e32 v99, v99
	v_add_u32_e32 v98, s19, v148
	v_add_f32_e32 v99, 1.0, v99
	v_rcp_f32_e32 v99, v99
	s_nop 0
	v_mul_f32_e32 v94, v94, v99
	v_mul_f32_e32 v90, v90, v94
	v_mul_f32_e32 v94, 0xbfb8aa3b, v95
	v_exp_f32_e32 v94, v94
	s_nop 0
	v_add_f32_e32 v94, 1.0, v94
	v_rcp_f32_e32 v94, v94
	s_nop 0
	v_mul_f32_e32 v94, v95, v94
	v_mul_f32_e32 v91, v91, v94
	v_cvt_pk_bf16_f32 v90, v90, v91
	v_mul_f32_e32 v91, 0xbfb8aa3b, v96
	v_exp_f32_e32 v91, v91
	s_nop 0
	v_add_f32_e32 v91, 1.0, v91
	v_rcp_f32_e32 v91, v91
	s_nop 0
	v_mul_f32_e32 v91, v96, v91
	v_mul_f32_e32 v91, v92, v91
	v_mul_f32_e32 v92, 0xbfb8aa3b, v97
	v_exp_f32_e32 v92, v92
	s_nop 0
	v_add_f32_e32 v92, 1.0, v92
	v_rcp_f32_e32 v92, v92
	s_nop 0
	v_mul_f32_e32 v92, v97, v92
	v_mul_f32_e32 v92, v93, v92
	v_cvt_pk_bf16_f32 v91, v91, v92
	s_nop 1
	s_nop 0
	s_nop 1
	s_nop 0
	s_nop 1
	s_nop 0
	s_nop 1
	s_nop 0
	s_nop 1
	s_nop 1
	s_nop 1
	s_nop 1
	v_mad_i64_i32 v[82:83], s[30:31], v98, s21, v[114:115]
	v_lshl_add_u64 v[82:83], v[82:83], 0, s[26:27]
	v_lshl_add_u64 v[82:83], v[82:83], 0, s[64:65]
	v_lshl_add_u64 v[82:83], v[82:83], 0, v[0:1]
	global_store_dwordx2 v[82:83], v[90:91], off
	s_nop 1
	v_mul_f32_e32 v83, 0xbfb8aa3b, v78
	v_exp_f32_e32 v83, v83
	v_add_u32_e32 v82, s19, v149
	v_add_f32_e32 v83, 1.0, v83
	v_rcp_f32_e32 v83, v83
	s_nop 0
	v_mul_f32_e32 v78, v78, v83
	v_mul_f32_e32 v74, v74, v78
	v_mul_f32_e32 v78, 0xbfb8aa3b, v79
	v_exp_f32_e32 v78, v78
	s_nop 0
	v_add_f32_e32 v78, 1.0, v78
	v_rcp_f32_e32 v78, v78
	s_nop 0
	v_mul_f32_e32 v78, v79, v78
	v_mul_f32_e32 v75, v75, v78
	v_cvt_pk_bf16_f32 v74, v74, v75
	v_mul_f32_e32 v75, 0xbfb8aa3b, v80
	v_exp_f32_e32 v75, v75
	s_nop 0
	v_add_f32_e32 v75, 1.0, v75
	v_rcp_f32_e32 v75, v75
	s_nop 0
	v_mul_f32_e32 v75, v80, v75
	v_mul_f32_e32 v75, v76, v75
	v_mul_f32_e32 v76, 0xbfb8aa3b, v81
	v_exp_f32_e32 v76, v76
	s_nop 0
	v_add_f32_e32 v76, 1.0, v76
	v_rcp_f32_e32 v76, v76
	s_nop 0
	v_mul_f32_e32 v76, v81, v76
	v_mul_f32_e32 v76, v77, v76
	v_cvt_pk_bf16_f32 v75, v75, v76
	s_nop 1
	s_nop 0
	s_nop 1
	s_nop 0
	s_nop 1
	s_nop 0
	s_nop 1
	s_nop 0
	s_nop 1
	s_nop 1
	s_nop 1
	s_nop 1
	v_mad_i64_i32 v[66:67], s[30:31], v82, s21, v[114:115]
	v_lshl_add_u64 v[66:67], v[66:67], 0, s[26:27]
	v_lshl_add_u64 v[66:67], v[66:67], 0, s[64:65]
	v_lshl_add_u64 v[66:67], v[66:67], 0, v[0:1]
	global_store_dwordx2 v[66:67], v[74:75], off
	s_nop 1
	v_add_u32_e32 v66, s19, v150
	s_nop 1
	s_nop 0
	s_nop 1
	s_nop 0
	s_nop 1
	s_nop 0
	s_nop 1
	s_nop 1
	s_nop 1
	s_nop 0
	s_nop 1
	s_nop 0
	s_nop 1
	s_nop 0
	s_nop 1
	s_nop 0
	s_nop 1
	s_nop 1
	s_nop 1
	s_nop 0
	s_nop 1
	s_nop 0
	s_nop 1
	s_nop 0
	s_nop 1
	s_nop 0
	s_nop 1
	s_nop 1
	s_nop 1
	s_nop 1
	v_mad_i64_i32 v[50:51], s[30:31], v66, s21, v[114:115]
	v_lshl_add_u64 v[50:51], v[50:51], 0, s[26:27]
; __device__ __forceinline__ unsigned pk2(float lo, float hi) { unsigned r; asm("v_cvt_pk_bf16_f32 %0, %1, %2" : "=v"(r) : "v"(lo), "v"(hi)); return r; }
; __device__ __forceinline__ float siluf(float v) { return v * __builtin_amdgcn_rcpf(1.f + __expf(-v)); }
;     __device__ __forceinline__ void operator()(const f32x4 (&acc)[2][2][4][2], const Unit& u, int wr, int wc, int fr, int fq) const {
; #pragma unroll
;         for (int ai = 0; ai < 2; ++ai)
; #pragma unroll
;             for (int m = 0; m < 4; ++m) {
;                 const int row = u.pm * 256 + ai * 128 + wr * 64 + m * 16 + fr;
;                 const f32x4 g0 = acc[ai][0][m][0], u0 = acc[ai][0][m][1], g1 = acc[ai][1][m][0], u1 = acc[ai][1][m][1];
;                 u32x4 w;
;                 w.x = pk2(siluf(g0[0]) * u0[0], siluf(g0[1]) * u0[1]); w.y = pk2(siluf(g0[2]) * u0[2], siluf(g0[3]) * u0[3]);
;                 w.z = pk2(siluf(g1[0]) * u1[0], siluf(g1[1]) * u1[1]); w.w = pk2(siluf(g1[2]) * u1[2], siluf(g1[3]) * u1[3]);
;                 *(u32x4*)(act + (size_t)row * DFF + u.pn * 128 + wc * 32 + 8 * fq) = w;
;             }
	v_lshl_add_u64 v[50:51], v[50:51], 0, s[64:65]
	v_lshl_add_u64 v[50:51], v[50:51], 0, v[0:1]
	s_nop 1
	v_add_u32_e32 v50, s19, v151
	s_nop 1
	s_nop 0
	s_nop 1
	s_nop 0
	s_nop 1
	s_nop 0
	s_nop 1
	s_nop 1
	s_nop 1
	s_nop 0
	s_nop 1
	s_nop 0
	s_nop 1
	s_nop 0
	s_nop 1
	s_nop 0
	s_nop 1
	s_nop 1
	s_nop 1
	s_nop 0
	s_nop 1
	s_nop 0
	s_nop 1
	s_nop 0
	s_nop 1
	s_nop 0
	s_nop 1
	s_nop 1
	s_nop 1
	s_nop 1
	v_mad_i64_i32 v[34:35], s[30:31], v50, s21, v[114:115]
	v_lshl_add_u64 v[34:35], v[34:35], 0, s[26:27]
	v_lshl_add_u64 v[34:35], v[34:35], 0, s[64:65]
	v_lshl_add_u64 v[34:35], v[34:35], 0, v[0:1]
	s_nop 1
	v_add_u32_e32 v34, s19, v152
	s_nop 1
	s_nop 0
	s_nop 1
	s_nop 0
	s_nop 1
	s_nop 0
	s_nop 1
	s_nop 1
	s_nop 1
	s_nop 0
	s_nop 1
	s_nop 0
	s_nop 1
	s_nop 0
	s_nop 1
	s_nop 0
	s_nop 1
	s_nop 1
	s_nop 1
	s_nop 0
	s_nop 1
	s_nop 0
	s_nop 1
	s_nop 0
	s_nop 1
	s_nop 0
	s_nop 1
	s_nop 1
	s_nop 1
	s_nop 1
	v_mad_i64_i32 v[18:19], s[30:31], v34, s21, v[114:115]
	v_lshl_add_u64 v[18:19], v[18:19], 0, s[26:27]
	v_lshl_add_u64 v[18:19], v[18:19], 0, s[64:65]
	v_lshl_add_u64 v[18:19], v[18:19], 0, v[0:1]
	s_nop 1
	v_add_u32_e32 v18, s19, v153
	s_nop 1
	s_nop 0
	s_nop 1
	s_nop 0
	s_nop 1
	s_nop 0
	s_nop 1
	s_nop 1
	s_nop 1
	s_nop 0
	s_nop 1
	s_nop 0
	s_nop 1
	s_nop 0
	s_nop 1
	s_nop 0
	s_nop 1
	s_nop 1
	s_nop 1
	s_nop 0
	s_nop 1
	s_nop 0
	s_nop 1
	s_nop 0
	s_nop 1
	s_nop 0
	s_nop 1
	s_nop 1
	s_nop 1
	s_nop 1
	v_mad_i64_i32 v[2:3], s[30:31], v18, s21, v[114:115]
	v_lshl_add_u64 v[2:3], v[2:3], 0, s[26:27]
	v_lshl_add_u64 v[2:3], v[2:3], 0, s[64:65]
	v_lshl_add_u64 v[2:3], v[2:3], 0, v[0:1]
	s_mov_b64 s[26:27], -1
	s_nop 1
	s_branch .Lku_epi_end
.Lkuq_epi2:
	s_nop 1
	s_lshl_b32 s19, s28, 8
	s_lshl_b32 s26, s26, 7
	v_add_u32_e32 v155, s19, v143
	s_nop 1
	s_movk_i32 s21, 0x1600
	s_ashr_i32 s27, s26, 31
	s_lshl_b64 s[26:27], s[26:27], 1
	s_nop 1
	s_andn2_b64 vcc, exec, s[6:7]
	s_nop 1
	s_nop 0
	s_nop 1
	s_nop 1
	s_nop 1
	s_nop 0
	s_nop 1
	s_nop 0
	s_nop 1
	s_nop 0
	s_nop 1
	s_nop 0
	s_nop 1
	s_nop 1
	s_nop 1
	s_nop 0
	s_nop 1
	s_nop 0
	s_nop 1
	s_nop 0
	s_nop 1
	s_nop 0
	s_nop 1
	s_nop 1
	s_nop 1
	s_nop 1
	v_mov_b64_e32 v[114:115], s[14:15]
	v_mad_i64_i32 v[116:117], s[30:31], v155, s21, v[114:115]
	v_lshl_add_u64 v[116:117], v[116:117], 0, s[26:27]
	v_lshl_add_u64 v[116:117], v[116:117], 0, s[64:65]
	v_lshl_add_u64 v[116:117], v[116:117], 0, v[0:1]
	s_nop 1
	v_add_u32_e32 v116, s19, v147
	s_nop 1
	s_nop 0
	s_nop 1
	s_nop 0
	s_nop 1
	s_nop 0
	s_nop 1
	s_nop 1
	s_nop 1
	s_nop 0
	s_nop 1
	s_nop 0
	s_nop 1
	s_nop 0
	s_nop 1
	s_nop 0
	s_nop 1
	s_nop 1
	s_nop 1
	s_nop 0
	s_nop 1
	s_nop 0
	s_nop 1
	s_nop 0
	s_nop 1
	s_nop 0
	s_nop 1
	s_nop 1
	s_nop 1
	s_nop 1
	v_mad_i64_i32 v[98:99], s[30:31], v116, s21, v[114:115]
	v_lshl_add_u64 v[98:99], v[98:99], 0, s[26:27]
	v_lshl_add_u64 v[98:99], v[98:99], 0, s[64:65]
	v_lshl_add_u64 v[98:99], v[98:99], 0, v[0:1]
	s_nop 1
	v_add_u32_e32 v98, s19, v148
	s_nop 1
	s_nop 0
	s_nop 1
	s_nop 0
	s_nop 1
	s_nop 0
	s_nop 1
	s_nop 1
	s_nop 1
	s_nop 0
	s_nop 1
	s_nop 0
	s_nop 1
	s_nop 0
	s_nop 1
	s_nop 0
	s_nop 1
	s_nop 1
	s_nop 1
	s_nop 0
	s_nop 1
	s_nop 0
	s_nop 1
	s_nop 0
	s_nop 1
	s_nop 0
	s_nop 1
	s_nop 1
	s_nop 1
	s_nop 1
	v_mad_i64_i32 v[82:83], s[30:31], v98, s21, v[114:115]
	v_lshl_add_u64 v[82:83], v[82:83], 0, s[26:27]
	v_lshl_add_u64 v[82:83], v[82:83], 0, s[64:65]
	v_lshl_add_u64 v[82:83], v[82:83], 0, v[0:1]
	s_nop 1
	v_add_u32_e32 v82, s19, v149
	s_nop 1
	s_nop 0
	s_nop 1
	s_nop 0
	s_nop 1
	s_nop 0
	s_nop 1
	s_nop 1
	s_nop 1
	s_nop 0
	s_nop 1
	s_nop 0
	s_nop 1
	s_nop 0
	s_nop 1
	s_nop 0
	s_nop 1
	s_nop 1
	s_nop 1
	s_nop 0
	s_nop 1
	s_nop 0
	s_nop 1
	s_nop 0
	s_nop 1
	s_nop 0
	s_nop 1
	s_nop 1
	s_nop 1
	s_nop 1
	v_mad_i64_i32 v[66:67], s[30:31], v82, s21, v[114:115]
	v_lshl_add_u64 v[66:67], v[66:67], 0, s[26:27]
	v_lshl_add_u64 v[66:67], v[66:67], 0, s[64:65]
	v_lshl_add_u64 v[66:67], v[66:67], 0, v[0:1]
	s_nop 1
	v_mul_f32_e32 v67, 0xbfb8aa3b, v62
	v_exp_f32_e32 v67, v67
	v_add_u32_e32 v66, s19, v150
	v_add_f32_e32 v67, 1.0, v67
	v_rcp_f32_e32 v67, v67
	s_nop 0
	v_mul_f32_e32 v62, v62, v67
	v_mul_f32_e32 v58, v58, v62
	v_mul_f32_e32 v62, 0xbfb8aa3b, v63
	v_exp_f32_e32 v62, v62
	s_nop 0
	v_add_f32_e32 v62, 1.0, v62
	v_rcp_f32_e32 v62, v62
	s_nop 0
	v_mul_f32_e32 v62, v63, v62
	v_mul_f32_e32 v59, v59, v62
	v_cvt_pk_bf16_f32 v58, v58, v59
	v_mul_f32_e32 v59, 0xbfb8aa3b, v64
	v_exp_f32_e32 v59, v59
	s_nop 0
	v_add_f32_e32 v59, 1.0, v59
	v_rcp_f32_e32 v59, v59
	s_nop 0
	v_mul_f32_e32 v59, v64, v59
	v_mul_f32_e32 v59, v60, v59
	v_mul_f32_e32 v60, 0xbfb8aa3b, v65
	v_exp_f32_e32 v60, v60
	s_nop 0
	v_add_f32_e32 v60, 1.0, v60
	v_rcp_f32_e32 v60, v60
	s_nop 0
	v_mul_f32_e32 v60, v65, v60
	v_mul_f32_e32 v60, v61, v60
	v_cvt_pk_bf16_f32 v59, v59, v60
	s_nop 1
	s_nop 0
	s_nop 1
	s_nop 0
	s_nop 1
	s_nop 0
	s_nop 1
	s_nop 0
	s_nop 1
	s_nop 1
	s_nop 1
	s_nop 1
	v_mad_i64_i32 v[50:51], s[30:31], v66, s21, v[114:115]
	v_lshl_add_u64 v[50:51], v[50:51], 0, s[26:27]
	v_lshl_add_u64 v[50:51], v[50:51], 0, s[64:65]
	v_lshl_add_u64 v[50:51], v[50:51], 0, v[0:1]
	global_store_dwordx2 v[50:51], v[58:59], off
	s_nop 1
	v_mul_f32_e32 v51, 0xbfb8aa3b, v46
	v_exp_f32_e32 v51, v51
	v_add_u32_e32 v50, s19, v151
	v_add_f32_e32 v51, 1.0, v51
	v_rcp_f32_e32 v51, v51
	s_nop 0
	v_mul_f32_e32 v46, v46, v51
	v_mul_f32_e32 v42, v42, v46
	v_mul_f32_e32 v46, 0xbfb8aa3b, v47
	v_exp_f32_e32 v46, v46
	s_nop 0
	v_add_f32_e32 v46, 1.0, v46
	v_rcp_f32_e32 v46, v46
	s_nop 0
	v_mul_f32_e32 v46, v47, v46
	v_mul_f32_e32 v43, v43, v46
	v_cvt_pk_bf16_f32 v42, v42, v43
	v_mul_f32_e32 v43, 0xbfb8aa3b, v48
	v_exp_f32_e32 v43, v43
	s_nop 0
	v_add_f32_e32 v43, 1.0, v43
; __device__ __forceinline__ unsigned pk2(float lo, float hi) { unsigned r; asm("v_cvt_pk_bf16_f32 %0, %1, %2" : "=v"(r) : "v"(lo), "v"(hi)); return r; }
; __device__ __forceinline__ float siluf(float v) { return v * __builtin_amdgcn_rcpf(1.f + __expf(-v)); }
;     __device__ __forceinline__ void operator()(const f32x4 (&acc)[2][2][4][2], const Unit& u, int wr, int wc, int fr, int fq) const {
; #pragma unroll
;         for (int ai = 0; ai < 2; ++ai)
; #pragma unroll
;             for (int m = 0; m < 4; ++m) {
;                 const int row = u.pm * 256 + ai * 128 + wr * 64 + m * 16 + fr;
;                 const f32x4 g0 = acc[ai][0][m][0], u0 = acc[ai][0][m][1], g1 = acc[ai][1][m][0], u1 = acc[ai][1][m][1];
;                 u32x4 w;
;                 w.x = pk2(siluf(g0[0]) * u0[0], siluf(g0[1]) * u0[1]); w.y = pk2(siluf(g0[2]) * u0[2], siluf(g0[3]) * u0[3]);
;                 w.z = pk2(siluf(g1[0]) * u1[0], siluf(g1[1]) * u1[1]); w.w = pk2(siluf(g1[2]) * u1[2], siluf(g1[3]) * u1[3]);
;                 *(u32x4*)(act + (size_t)row * DFF + u.pn * 128 + wc * 32 + 8 * fq) = w;
;             }
;     }
	v_rcp_f32_e32 v43, v43
	s_nop 0
	v_mul_f32_e32 v43, v48, v43
	v_mul_f32_e32 v43, v44, v43
	v_mul_f32_e32 v44, 0xbfb8aa3b, v49
	v_exp_f32_e32 v44, v44
	s_nop 0
	v_add_f32_e32 v44, 1.0, v44
	v_rcp_f32_e32 v44, v44
	s_nop 0
	v_mul_f32_e32 v44, v49, v44
	v_mul_f32_e32 v44, v45, v44
	v_cvt_pk_bf16_f32 v43, v43, v44
	s_nop 1
	s_nop 0
	s_nop 1
	s_nop 0
	s_nop 1
	s_nop 0
	s_nop 1
	s_nop 0
	s_nop 1
	s_nop 1
	s_nop 1
	s_nop 1
	v_mad_i64_i32 v[34:35], s[30:31], v50, s21, v[114:115]
	v_lshl_add_u64 v[34:35], v[34:35], 0, s[26:27]
	v_lshl_add_u64 v[34:35], v[34:35], 0, s[64:65]
	v_lshl_add_u64 v[34:35], v[34:35], 0, v[0:1]
	global_store_dwordx2 v[34:35], v[42:43], off
	s_nop 1
	v_mul_f32_e32 v35, 0xbfb8aa3b, v30
	v_exp_f32_e32 v35, v35
	v_add_u32_e32 v34, s19, v152
	v_add_f32_e32 v35, 1.0, v35
	v_rcp_f32_e32 v35, v35
	s_nop 0
	v_mul_f32_e32 v30, v30, v35
	v_mul_f32_e32 v26, v26, v30
	v_mul_f32_e32 v30, 0xbfb8aa3b, v31
	v_exp_f32_e32 v30, v30
	s_nop 0
	v_add_f32_e32 v30, 1.0, v30
	v_rcp_f32_e32 v30, v30
	s_nop 0
	v_mul_f32_e32 v30, v31, v30
	v_mul_f32_e32 v27, v27, v30
	v_cvt_pk_bf16_f32 v26, v26, v27
	v_mul_f32_e32 v27, 0xbfb8aa3b, v32
	v_exp_f32_e32 v27, v27
	s_nop 0
	v_add_f32_e32 v27, 1.0, v27
	v_rcp_f32_e32 v27, v27
	s_nop 0
	v_mul_f32_e32 v27, v32, v27
	v_mul_f32_e32 v27, v28, v27
	v_mul_f32_e32 v28, 0xbfb8aa3b, v33
	v_exp_f32_e32 v28, v28
	s_nop 0
	v_add_f32_e32 v28, 1.0, v28
	v_rcp_f32_e32 v28, v28
	s_nop 0
	v_mul_f32_e32 v28, v33, v28
	v_mul_f32_e32 v28, v29, v28
	v_cvt_pk_bf16_f32 v27, v27, v28
	s_nop 1
	s_nop 0
	s_nop 1
	s_nop 0
	s_nop 1
	s_nop 0
	s_nop 1
	s_nop 0
	s_nop 1
	s_nop 1
	s_nop 1
	s_nop 1
	v_mad_i64_i32 v[18:19], s[30:31], v34, s21, v[114:115]
	v_lshl_add_u64 v[18:19], v[18:19], 0, s[26:27]
	v_lshl_add_u64 v[18:19], v[18:19], 0, s[64:65]
	v_lshl_add_u64 v[18:19], v[18:19], 0, v[0:1]
	global_store_dwordx2 v[18:19], v[26:27], off
	s_nop 1
	v_mul_f32_e32 v19, 0xbfb8aa3b, v14
	v_exp_f32_e32 v19, v19
	v_add_u32_e32 v18, s19, v153
	v_add_f32_e32 v19, 1.0, v19
	v_rcp_f32_e32 v19, v19
	s_nop 0
	v_mul_f32_e32 v14, v14, v19
	v_mul_f32_e32 v10, v10, v14
	v_mul_f32_e32 v14, 0xbfb8aa3b, v15
	v_exp_f32_e32 v14, v14
	s_nop 0
	v_add_f32_e32 v14, 1.0, v14
	v_rcp_f32_e32 v14, v14
	s_nop 0
	v_mul_f32_e32 v14, v15, v14
	v_mul_f32_e32 v11, v11, v14
	v_cvt_pk_bf16_f32 v10, v10, v11
	v_mul_f32_e32 v11, 0xbfb8aa3b, v16
	v_exp_f32_e32 v11, v11
	s_nop 0
	v_add_f32_e32 v11, 1.0, v11
	v_rcp_f32_e32 v11, v11
	s_nop 0
	v_mul_f32_e32 v11, v16, v11
	v_mul_f32_e32 v11, v12, v11
	v_mul_f32_e32 v12, 0xbfb8aa3b, v17
	v_exp_f32_e32 v12, v12
	s_nop 0
	v_add_f32_e32 v12, 1.0, v12
	v_rcp_f32_e32 v12, v12
	s_nop 0
	v_mul_f32_e32 v12, v17, v12
	v_mul_f32_e32 v12, v13, v12
	v_cvt_pk_bf16_f32 v11, v11, v12
	s_nop 1
	s_nop 0
	s_nop 1
	s_nop 0
	s_nop 1
	s_nop 0
	s_nop 1
	s_nop 0
	s_nop 1
	s_nop 1
	s_nop 1
	s_nop 1
	v_mad_i64_i32 v[2:3], s[30:31], v18, s21, v[114:115]
	v_lshl_add_u64 v[2:3], v[2:3], 0, s[26:27]
	v_lshl_add_u64 v[2:3], v[2:3], 0, s[64:65]
	v_lshl_add_u64 v[2:3], v[2:3], 0, v[0:1]
	s_mov_b64 s[26:27], -1
	global_store_dwordx2 v[2:3], v[10:11], off
	s_nop 1
	s_branch .Lku_epi_end
.Lkuq_epi3:
	s_nop 1
	s_lshl_b32 s19, s28, 8
	s_lshl_b32 s26, s26, 7
	v_add_u32_e32 v155, s19, v143
	s_nop 1
	s_movk_i32 s21, 0x1600
	s_ashr_i32 s27, s26, 31
	s_lshl_b64 s[26:27], s[26:27], 1
	s_nop 1
	s_andn2_b64 vcc, exec, s[6:7]
	s_nop 1
	s_nop 0
	s_nop 1
	s_nop 1
	s_nop 1
	s_nop 0
	s_nop 1
	s_nop 0
	s_nop 1
	s_nop 0
	s_nop 1
	s_nop 0
	s_nop 1
	s_nop 1
	v_mul_f32_e32 v124, 0xbfb8aa3b, v118
	v_exp_f32_e32 v124, v124
	s_nop 0
	v_add_f32_e32 v124, 1.0, v124
	v_rcp_f32_e32 v124, v124
	s_nop 0
	v_mul_f32_e32 v118, v118, v124
	v_mul_f32_e32 v114, v114, v118
	v_mul_f32_e32 v118, 0xbfb8aa3b, v119
	v_exp_f32_e32 v118, v118
	s_nop 0
	v_add_f32_e32 v118, 1.0, v118
	v_rcp_f32_e32 v118, v118
	s_nop 0
	v_mul_f32_e32 v118, v119, v118
	v_mul_f32_e32 v115, v115, v118
	v_cvt_pk_bf16_f32 v124, v114, v115
	v_mul_f32_e32 v114, 0xbfb8aa3b, v120
	v_mul_f32_e32 v115, 0xbfb8aa3b, v121
	v_exp_f32_e32 v114, v114
	v_exp_f32_e32 v115, v115
	v_add_f32_e32 v114, 1.0, v114
	v_add_f32_e32 v115, 1.0, v115
	v_rcp_f32_e32 v114, v114
	v_rcp_f32_e32 v115, v115
	v_mul_f32_e32 v114, v120, v114
	v_mul_f32_e32 v115, v121, v115
	v_mul_f32_e32 v114, v116, v114
	v_mul_f32_e32 v115, v117, v115
	v_cvt_pk_bf16_f32 v125, v114, v115
	v_mov_b64_e32 v[114:115], s[14:15]
	v_mad_i64_i32 v[116:117], s[30:31], v155, s21, v[114:115]
	v_lshl_add_u64 v[116:117], v[116:117], 0, s[26:27]
	v_lshl_add_u64 v[116:117], v[116:117], 0, s[64:65]
	v_lshl_add_u64 v[116:117], v[116:117], 0, v[0:1]
	s_nop 1
	global_store_dwordx2 v[116:117], v[124:125], off offset:8
	s_nop 1
	v_add_u32_e32 v116, s19, v147
	s_nop 1
	s_nop 0
	s_nop 1
	s_nop 0
	s_nop 1
	s_nop 0
	s_nop 1
	s_nop 1
	s_nop 1
	s_nop 0
	s_nop 1
	s_nop 0
	s_nop 1
	s_nop 0
	s_nop 1
	s_nop 0
	s_nop 1
	s_nop 1
	v_mul_f32_e32 v108, 0xbfb8aa3b, v102
	v_exp_f32_e32 v108, v108
	s_nop 0
	v_add_f32_e32 v108, 1.0, v108
	v_rcp_f32_e32 v108, v108
	s_nop 0
	v_mul_f32_e32 v102, v102, v108
	v_mul_f32_e32 v98, v98, v102
	v_mul_f32_e32 v102, 0xbfb8aa3b, v103
	v_exp_f32_e32 v102, v102
	s_nop 0
	v_add_f32_e32 v102, 1.0, v102
	v_rcp_f32_e32 v102, v102
	s_nop 0
	v_mul_f32_e32 v102, v103, v102
	v_mul_f32_e32 v99, v99, v102
	v_cvt_pk_bf16_f32 v108, v98, v99
	v_mul_f32_e32 v98, 0xbfb8aa3b, v104
	v_mul_f32_e32 v99, 0xbfb8aa3b, v105
	v_exp_f32_e32 v98, v98
	v_exp_f32_e32 v99, v99
	v_add_f32_e32 v98, 1.0, v98
	v_add_f32_e32 v99, 1.0, v99
	v_rcp_f32_e32 v98, v98
	v_rcp_f32_e32 v99, v99
	v_mul_f32_e32 v98, v104, v98
	v_mul_f32_e32 v99, v105, v99
	v_mul_f32_e32 v98, v100, v98
	v_mul_f32_e32 v99, v101, v99
	v_cvt_pk_bf16_f32 v109, v98, v99
; __device__ __forceinline__ unsigned pk2(float lo, float hi) { unsigned r; asm("v_cvt_pk_bf16_f32 %0, %1, %2" : "=v"(r) : "v"(lo), "v"(hi)); return r; }
; __device__ __forceinline__ float siluf(float v) { return v * __builtin_amdgcn_rcpf(1.f + __expf(-v)); }
;     __device__ __forceinline__ void operator()(const f32x4 (&acc)[2][2][4][2], const Unit& u, int wr, int wc, int fr, int fq) const {
; #pragma unroll
;         for (int ai = 0; ai < 2; ++ai)
; #pragma unroll
;             for (int m = 0; m < 4; ++m) {
;                 const int row = u.pm * 256 + ai * 128 + wr * 64 + m * 16 + fr;
;                 const f32x4 g0 = acc[ai][0][m][0], u0 = acc[ai][0][m][1], g1 = acc[ai][1][m][0], u1 = acc[ai][1][m][1];
;                 u32x4 w;
;                 w.x = pk2(siluf(g0[0]) * u0[0], siluf(g0[1]) * u0[1]); w.y = pk2(siluf(g0[2]) * u0[2], siluf(g0[3]) * u0[3]);
;                 w.z = pk2(siluf(g1[0]) * u1[0], siluf(g1[1]) * u1[1]); w.w = pk2(siluf(g1[2]) * u1[2], siluf(g1[3]) * u1[3]);
;                 *(u32x4*)(act + (size_t)row * DFF + u.pn * 128 + wc * 32 + 8 * fq) = w;
;             }
;     }
	v_mad_i64_i32 v[98:99], s[30:31], v116, s21, v[114:115]
	v_lshl_add_u64 v[98:99], v[98:99], 0, s[26:27]
	v_lshl_add_u64 v[98:99], v[98:99], 0, s[64:65]
	v_lshl_add_u64 v[98:99], v[98:99], 0, v[0:1]
	s_nop 1
	global_store_dwordx2 v[98:99], v[108:109], off offset:8
	s_nop 1
	v_add_u32_e32 v98, s19, v148
	s_nop 1
	s_nop 0
	s_nop 1
	s_nop 0
	s_nop 1
	s_nop 0
	s_nop 1
	s_nop 1
	s_nop 1
	s_nop 0
	s_nop 1
	s_nop 0
	s_nop 1
	s_nop 0
	s_nop 1
	s_nop 0
	s_nop 1
	s_nop 1
	v_mul_f32_e32 v92, 0xbfb8aa3b, v86
	v_exp_f32_e32 v92, v92
	s_nop 0
	v_add_f32_e32 v92, 1.0, v92
	v_rcp_f32_e32 v92, v92
	s_nop 0
	v_mul_f32_e32 v86, v86, v92
	v_mul_f32_e32 v82, v82, v86
	v_mul_f32_e32 v86, 0xbfb8aa3b, v87
	v_exp_f32_e32 v86, v86
	s_nop 0
	v_add_f32_e32 v86, 1.0, v86
	v_rcp_f32_e32 v86, v86
	s_nop 0
	v_mul_f32_e32 v86, v87, v86
	v_mul_f32_e32 v83, v83, v86
	v_cvt_pk_bf16_f32 v92, v82, v83
	v_mul_f32_e32 v82, 0xbfb8aa3b, v88
	v_mul_f32_e32 v83, 0xbfb8aa3b, v89
	v_exp_f32_e32 v82, v82
	v_exp_f32_e32 v83, v83
	v_add_f32_e32 v82, 1.0, v82
	v_add_f32_e32 v83, 1.0, v83
	v_rcp_f32_e32 v82, v82
	v_rcp_f32_e32 v83, v83
	v_mul_f32_e32 v82, v88, v82
	v_mul_f32_e32 v83, v89, v83
	v_mul_f32_e32 v82, v84, v82
	v_mul_f32_e32 v83, v85, v83
	v_cvt_pk_bf16_f32 v93, v82, v83
	v_mad_i64_i32 v[82:83], s[30:31], v98, s21, v[114:115]
	v_lshl_add_u64 v[82:83], v[82:83], 0, s[26:27]
	v_lshl_add_u64 v[82:83], v[82:83], 0, s[64:65]
	v_lshl_add_u64 v[82:83], v[82:83], 0, v[0:1]
	s_nop 1
	global_store_dwordx2 v[82:83], v[92:93], off offset:8
	s_nop 1
	v_add_u32_e32 v82, s19, v149
	s_nop 1
	s_nop 0
	s_nop 1
	s_nop 0
	s_nop 1
	s_nop 0
	s_nop 1
	s_nop 1
	s_nop 1
	s_nop 0
	s_nop 1
	s_nop 0
	s_nop 1
	s_nop 0
	s_nop 1
	s_nop 0
	s_nop 1
	s_nop 1
	v_mul_f32_e32 v76, 0xbfb8aa3b, v70
	v_exp_f32_e32 v76, v76
	s_nop 0
	v_add_f32_e32 v76, 1.0, v76
	v_rcp_f32_e32 v76, v76
	s_nop 0
	v_mul_f32_e32 v70, v70, v76
	v_mul_f32_e32 v66, v66, v70
	v_mul_f32_e32 v70, 0xbfb8aa3b, v71
	v_exp_f32_e32 v70, v70
	s_nop 0
	v_add_f32_e32 v70, 1.0, v70
	v_rcp_f32_e32 v70, v70
	s_nop 0
	v_mul_f32_e32 v70, v71, v70
	v_mul_f32_e32 v67, v67, v70
	v_cvt_pk_bf16_f32 v76, v66, v67
	v_mul_f32_e32 v66, 0xbfb8aa3b, v72
	v_mul_f32_e32 v67, 0xbfb8aa3b, v73
	v_exp_f32_e32 v66, v66
	v_exp_f32_e32 v67, v67
	v_add_f32_e32 v66, 1.0, v66
	v_add_f32_e32 v67, 1.0, v67
	v_rcp_f32_e32 v66, v66
	v_rcp_f32_e32 v67, v67
	v_mul_f32_e32 v66, v72, v66
	v_mul_f32_e32 v67, v73, v67
	v_mul_f32_e32 v66, v68, v66
	v_mul_f32_e32 v67, v69, v67
	v_cvt_pk_bf16_f32 v77, v66, v67
	v_mad_i64_i32 v[66:67], s[30:31], v82, s21, v[114:115]
	v_lshl_add_u64 v[66:67], v[66:67], 0, s[26:27]
	v_lshl_add_u64 v[66:67], v[66:67], 0, s[64:65]
	v_lshl_add_u64 v[66:67], v[66:67], 0, v[0:1]
	s_nop 1
	global_store_dwordx2 v[66:67], v[76:77], off offset:8
	s_nop 1
	v_add_u32_e32 v66, s19, v150
	s_nop 1
	s_nop 0
	s_nop 1
	s_nop 0
	s_nop 1
	s_nop 0
	s_nop 1
	s_nop 1
	s_nop 1
	s_nop 0
	s_nop 1
	s_nop 0
	s_nop 1
	s_nop 0
	s_nop 1
	s_nop 0
	s_nop 1
	s_nop 1
	s_nop 1
	s_nop 0
	s_nop 1
	s_nop 0
	s_nop 1
	s_nop 0
	s_nop 1
	s_nop 0
	s_nop 1
	s_nop 1
	s_nop 1
	s_nop 1
	v_mad_i64_i32 v[50:51], s[30:31], v66, s21, v[114:115]
	v_lshl_add_u64 v[50:51], v[50:51], 0, s[26:27]
	v_lshl_add_u64 v[50:51], v[50:51], 0, s[64:65]
	v_lshl_add_u64 v[50:51], v[50:51], 0, v[0:1]
	s_nop 1
	v_add_u32_e32 v50, s19, v151
	s_nop 1
	s_nop 0
	s_nop 1
	s_nop 0
	s_nop 1
	s_nop 0
	s_nop 1
	s_nop 1
	s_nop 1
	s_nop 0
	s_nop 1
	s_nop 0
	s_nop 1
	s_nop 0
	s_nop 1
	s_nop 0
	s_nop 1
	s_nop 1
	s_nop 1
	s_nop 0
	s_nop 1
	s_nop 0
	s_nop 1
	s_nop 0
	s_nop 1
	s_nop 0
	s_nop 1
	s_nop 1
	s_nop 1
	s_nop 1
	v_mad_i64_i32 v[34:35], s[30:31], v50, s21, v[114:115]
	v_lshl_add_u64 v[34:35], v[34:35], 0, s[26:27]
	v_lshl_add_u64 v[34:35], v[34:35], 0, s[64:65]
	v_lshl_add_u64 v[34:35], v[34:35], 0, v[0:1]
	s_nop 1
	v_add_u32_e32 v34, s19, v152
	s_nop 1
	s_nop 0
	s_nop 1
	s_nop 0
	s_nop 1
	s_nop 0
	s_nop 1
	s_nop 1
	s_nop 1
	s_nop 0
	s_nop 1
	s_nop 0
	s_nop 1
	s_nop 0
	s_nop 1
	s_nop 0
	s_nop 1
	s_nop 1
	s_nop 1
	s_nop 0
	s_nop 1
	s_nop 0
	s_nop 1
	s_nop 0
	s_nop 1
	s_nop 0
	s_nop 1
	s_nop 1
	s_nop 1
	s_nop 1
	v_mad_i64_i32 v[18:19], s[30:31], v34, s21, v[114:115]
	v_lshl_add_u64 v[18:19], v[18:19], 0, s[26:27]
	v_lshl_add_u64 v[18:19], v[18:19], 0, s[64:65]
	v_lshl_add_u64 v[18:19], v[18:19], 0, v[0:1]
	s_nop 1
	v_add_u32_e32 v18, s19, v153
	s_nop 1
	s_nop 0
	s_nop 1
	s_nop 0
	s_nop 1
	s_nop 0
	s_nop 1
	s_nop 1
	s_nop 1
	s_nop 0
	s_nop 1
	s_nop 0
	s_nop 1
	s_nop 0
	s_nop 1
	s_nop 0
	s_nop 1
	s_nop 1
	s_nop 1
	s_nop 0
	s_nop 1
	s_nop 0
	s_nop 1
	s_nop 0
	s_nop 1
	s_nop 0
	s_nop 1
	s_nop 1
	s_nop 1
	s_nop 1
	v_mad_i64_i32 v[2:3], s[30:31], v18, s21, v[114:115]
	v_lshl_add_u64 v[2:3], v[2:3], 0, s[26:27]
	v_lshl_add_u64 v[2:3], v[2:3], 0, s[64:65]
	v_lshl_add_u64 v[2:3], v[2:3], 0, v[0:1]
	s_mov_b64 s[26:27], -1
	s_nop 1
	s_branch .Lku_epi_end
; __device__ __forceinline__ unsigned pk2(float lo, float hi) { unsigned r; asm("v_cvt_pk_bf16_f32 %0, %1, %2" : "=v"(r) : "v"(lo), "v"(hi)); return r; }
; __device__ __forceinline__ float siluf(float v) { return v * __builtin_amdgcn_rcpf(1.f + __expf(-v)); }
;     __device__ __forceinline__ void operator()(const f32x4 (&acc)[2][2][4][2], const Unit& u, int wr, int wc, int fr, int fq) const {
; #pragma unroll
;         for (int ai = 0; ai < 2; ++ai)
; #pragma unroll
;             for (int m = 0; m < 4; ++m) {
;                 const int row = u.pm * 256 + ai * 128 + wr * 64 + m * 16 + fr;
;                 const f32x4 g0 = acc[ai][0][m][0], u0 = acc[ai][0][m][1], g1 = acc[ai][1][m][0], u1 = acc[ai][1][m][1];
;                 u32x4 w;
;                 w.x = pk2(siluf(g0[0]) * u0[0], siluf(g0[1]) * u0[1]); w.y = pk2(siluf(g0[2]) * u0[2], siluf(g0[3]) * u0[3]);
;                 w.z = pk2(siluf(g1[0]) * u1[0], siluf(g1[1]) * u1[1]); w.w = pk2(siluf(g1[2]) * u1[2], siluf(g1[3]) * u1[3]);
;                 *(u32x4*)(act + (size_t)row * DFF + u.pn * 128 + wc * 32 + 8 * fq) = w;
;             }
;     }
.Lkuq_epi4:
	s_nop 1
	s_lshl_b32 s19, s28, 8
	s_lshl_b32 s26, s26, 7
	v_add_u32_e32 v155, s19, v143
	s_nop 1
	s_movk_i32 s21, 0x1600
	s_ashr_i32 s27, s26, 31
	s_lshl_b64 s[26:27], s[26:27], 1
	s_nop 1
	s_andn2_b64 vcc, exec, s[6:7]
	s_nop 1
	s_nop 0
	s_nop 1
	s_nop 1
	s_nop 1
	s_nop 0
	s_nop 1
	s_nop 0
	s_nop 1
	s_nop 0
	s_nop 1
	s_nop 0
	s_nop 1
	s_nop 1
	s_nop 1
	s_nop 0
	s_nop 1
	s_nop 0
	s_nop 1
	s_nop 0
	s_nop 1
	s_nop 0
	s_nop 1
	s_nop 1
	s_nop 1
	s_nop 1
	v_mov_b64_e32 v[114:115], s[14:15]
	v_mad_i64_i32 v[116:117], s[30:31], v155, s21, v[114:115]
	v_lshl_add_u64 v[116:117], v[116:117], 0, s[26:27]
	v_lshl_add_u64 v[116:117], v[116:117], 0, s[64:65]
	v_lshl_add_u64 v[116:117], v[116:117], 0, v[0:1]
	s_nop 1
	v_add_u32_e32 v116, s19, v147
	s_nop 1
	s_nop 0
	s_nop 1
	s_nop 0
	s_nop 1
	s_nop 0
	s_nop 1
	s_nop 1
	s_nop 1
	s_nop 0
	s_nop 1
	s_nop 0
	s_nop 1
	s_nop 0
	s_nop 1
	s_nop 0
	s_nop 1
	s_nop 1
	s_nop 1
	s_nop 0
	s_nop 1
	s_nop 0
	s_nop 1
	s_nop 0
	s_nop 1
	s_nop 0
	s_nop 1
	s_nop 1
	s_nop 1
	s_nop 1
	v_mad_i64_i32 v[98:99], s[30:31], v116, s21, v[114:115]
	v_lshl_add_u64 v[98:99], v[98:99], 0, s[26:27]
	v_lshl_add_u64 v[98:99], v[98:99], 0, s[64:65]
	v_lshl_add_u64 v[98:99], v[98:99], 0, v[0:1]
	s_nop 1
	v_add_u32_e32 v98, s19, v148
	s_nop 1
	s_nop 0
	s_nop 1
	s_nop 0
	s_nop 1
	s_nop 0
	s_nop 1
	s_nop 1
	s_nop 1
	s_nop 0
	s_nop 1
	s_nop 0
	s_nop 1
	s_nop 0
	s_nop 1
	s_nop 0
	s_nop 1
	s_nop 1
	s_nop 1
	s_nop 0
	s_nop 1
	s_nop 0
	s_nop 1
	s_nop 0
	s_nop 1
	s_nop 0
	s_nop 1
	s_nop 1
	s_nop 1
	s_nop 1
	v_mad_i64_i32 v[82:83], s[30:31], v98, s21, v[114:115]
	v_lshl_add_u64 v[82:83], v[82:83], 0, s[26:27]
	v_lshl_add_u64 v[82:83], v[82:83], 0, s[64:65]
	v_lshl_add_u64 v[82:83], v[82:83], 0, v[0:1]
	s_nop 1
	v_add_u32_e32 v82, s19, v149
	s_nop 1
	s_nop 0
	s_nop 1
	s_nop 0
	s_nop 1
	s_nop 0
	s_nop 1
	s_nop 1
	s_nop 1
	s_nop 0
	s_nop 1
	s_nop 0
	s_nop 1
	s_nop 0
	s_nop 1
	s_nop 0
	s_nop 1
	s_nop 1
	s_nop 1
	s_nop 0
	s_nop 1
	s_nop 0
	s_nop 1
	s_nop 0
	s_nop 1
	s_nop 0
	s_nop 1
	s_nop 1
	s_nop 1
	s_nop 1
	v_mad_i64_i32 v[66:67], s[30:31], v82, s21, v[114:115]
	v_lshl_add_u64 v[66:67], v[66:67], 0, s[26:27]
	v_lshl_add_u64 v[66:67], v[66:67], 0, s[64:65]
	v_lshl_add_u64 v[66:67], v[66:67], 0, v[0:1]
	s_nop 1
	v_add_u32_e32 v66, s19, v150
	s_nop 1
	s_nop 0
	s_nop 1
	s_nop 0
	s_nop 1
	s_nop 0
	s_nop 1
	s_nop 1
	s_nop 1
	s_nop 0
	s_nop 1
	s_nop 0
	s_nop 1
	s_nop 0
	s_nop 1
	s_nop 0
	s_nop 1
	s_nop 1
	v_mul_f32_e32 v60, 0xbfb8aa3b, v54
	v_exp_f32_e32 v60, v60
	s_nop 0
	v_add_f32_e32 v60, 1.0, v60
	v_rcp_f32_e32 v60, v60
	s_nop 0
	v_mul_f32_e32 v54, v54, v60
	v_mul_f32_e32 v50, v50, v54
	v_mul_f32_e32 v54, 0xbfb8aa3b, v55
	v_exp_f32_e32 v54, v54
	s_nop 0
	v_add_f32_e32 v54, 1.0, v54
	v_rcp_f32_e32 v54, v54
	s_nop 0
	v_mul_f32_e32 v54, v55, v54
	v_mul_f32_e32 v51, v51, v54
	v_cvt_pk_bf16_f32 v60, v50, v51
	v_mul_f32_e32 v50, 0xbfb8aa3b, v56
	v_mul_f32_e32 v51, 0xbfb8aa3b, v57
	v_exp_f32_e32 v50, v50
	v_exp_f32_e32 v51, v51
	v_add_f32_e32 v50, 1.0, v50
	v_add_f32_e32 v51, 1.0, v51
	v_rcp_f32_e32 v50, v50
	v_rcp_f32_e32 v51, v51
	v_mul_f32_e32 v50, v56, v50
	v_mul_f32_e32 v51, v57, v51
	v_mul_f32_e32 v50, v52, v50
	v_mul_f32_e32 v51, v53, v51
	v_cvt_pk_bf16_f32 v61, v50, v51
	v_mad_i64_i32 v[50:51], s[30:31], v66, s21, v[114:115]
	v_lshl_add_u64 v[50:51], v[50:51], 0, s[26:27]
	v_lshl_add_u64 v[50:51], v[50:51], 0, s[64:65]
	v_lshl_add_u64 v[50:51], v[50:51], 0, v[0:1]
	s_nop 1
	global_store_dwordx2 v[50:51], v[60:61], off offset:8
	s_nop 1
	v_add_u32_e32 v50, s19, v151
	s_nop 1
	s_nop 0
	s_nop 1
	s_nop 0
	s_nop 1
	s_nop 0
	s_nop 1
	s_nop 1
; __device__ __forceinline__ unsigned pk2(float lo, float hi) { unsigned r; asm("v_cvt_pk_bf16_f32 %0, %1, %2" : "=v"(r) : "v"(lo), "v"(hi)); return r; }
; __device__ __forceinline__ float siluf(float v) { return v * __builtin_amdgcn_rcpf(1.f + __expf(-v)); }
;     __device__ __forceinline__ void operator()(const f32x4 (&acc)[2][2][4][2], const Unit& u, int wr, int wc, int fr, int fq) const {
; #pragma unroll
;         for (int ai = 0; ai < 2; ++ai)
; #pragma unroll
;             for (int m = 0; m < 4; ++m) {
;                 const int row = u.pm * 256 + ai * 128 + wr * 64 + m * 16 + fr;
;                 const f32x4 g0 = acc[ai][0][m][0], u0 = acc[ai][0][m][1], g1 = acc[ai][1][m][0], u1 = acc[ai][1][m][1];
;                 u32x4 w;
;                 w.x = pk2(siluf(g0[0]) * u0[0], siluf(g0[1]) * u0[1]); w.y = pk2(siluf(g0[2]) * u0[2], siluf(g0[3]) * u0[3]);
;                 w.z = pk2(siluf(g1[0]) * u1[0], siluf(g1[1]) * u1[1]); w.w = pk2(siluf(g1[2]) * u1[2], siluf(g1[3]) * u1[3]);
;                 *(u32x4*)(act + (size_t)row * DFF + u.pn * 128 + wc * 32 + 8 * fq) = w;
;             }
;     }
	s_nop 1
	s_nop 0
	s_nop 1
	s_nop 0
	s_nop 1
	s_nop 0
	s_nop 1
	s_nop 0
	s_nop 1
	s_nop 1
	v_mul_f32_e32 v44, 0xbfb8aa3b, v38
	v_exp_f32_e32 v44, v44
	s_nop 0
	v_add_f32_e32 v44, 1.0, v44
	v_rcp_f32_e32 v44, v44
	s_nop 0
	v_mul_f32_e32 v38, v38, v44
	v_mul_f32_e32 v34, v34, v38
	v_mul_f32_e32 v38, 0xbfb8aa3b, v39
	v_exp_f32_e32 v38, v38
	s_nop 0
	v_add_f32_e32 v38, 1.0, v38
	v_rcp_f32_e32 v38, v38
	s_nop 0
	v_mul_f32_e32 v38, v39, v38
	v_mul_f32_e32 v35, v35, v38
	v_cvt_pk_bf16_f32 v44, v34, v35
	v_mul_f32_e32 v34, 0xbfb8aa3b, v40
	v_mul_f32_e32 v35, 0xbfb8aa3b, v41
	v_exp_f32_e32 v34, v34
	v_exp_f32_e32 v35, v35
	v_add_f32_e32 v34, 1.0, v34
	v_add_f32_e32 v35, 1.0, v35
	v_rcp_f32_e32 v34, v34
	v_rcp_f32_e32 v35, v35
	v_mul_f32_e32 v34, v40, v34
	v_mul_f32_e32 v35, v41, v35
	v_mul_f32_e32 v34, v36, v34
	v_mul_f32_e32 v35, v37, v35
	v_cvt_pk_bf16_f32 v45, v34, v35
	v_mad_i64_i32 v[34:35], s[30:31], v50, s21, v[114:115]
	v_lshl_add_u64 v[34:35], v[34:35], 0, s[26:27]
	v_lshl_add_u64 v[34:35], v[34:35], 0, s[64:65]
	v_lshl_add_u64 v[34:35], v[34:35], 0, v[0:1]
	s_nop 1
	global_store_dwordx2 v[34:35], v[44:45], off offset:8
	s_nop 1
	v_add_u32_e32 v34, s19, v152
	s_nop 1
	s_nop 0
	s_nop 1
	s_nop 0
	s_nop 1
	s_nop 0
	s_nop 1
	s_nop 1
	s_nop 1
	s_nop 0
	s_nop 1
	s_nop 0
	s_nop 1
	s_nop 0
	s_nop 1
	s_nop 0
	s_nop 1
	s_nop 1
	v_mul_f32_e32 v28, 0xbfb8aa3b, v22
	v_exp_f32_e32 v28, v28
	s_nop 0
	v_add_f32_e32 v28, 1.0, v28
	v_rcp_f32_e32 v28, v28
	s_nop 0
	v_mul_f32_e32 v22, v22, v28
	v_mul_f32_e32 v18, v18, v22
	v_mul_f32_e32 v22, 0xbfb8aa3b, v23
	v_exp_f32_e32 v22, v22
	s_nop 0
	v_add_f32_e32 v22, 1.0, v22
	v_rcp_f32_e32 v22, v22
	s_nop 0
	v_mul_f32_e32 v22, v23, v22
	v_mul_f32_e32 v19, v19, v22
	v_cvt_pk_bf16_f32 v28, v18, v19
	v_mul_f32_e32 v18, 0xbfb8aa3b, v24
	v_mul_f32_e32 v19, 0xbfb8aa3b, v25
	v_exp_f32_e32 v18, v18
	v_exp_f32_e32 v19, v19
	v_add_f32_e32 v18, 1.0, v18
	v_add_f32_e32 v19, 1.0, v19
	v_rcp_f32_e32 v18, v18
	v_rcp_f32_e32 v19, v19
	v_mul_f32_e32 v18, v24, v18
	v_mul_f32_e32 v19, v25, v19
	v_mul_f32_e32 v18, v20, v18
	v_mul_f32_e32 v19, v21, v19
	v_cvt_pk_bf16_f32 v29, v18, v19
	v_mad_i64_i32 v[18:19], s[30:31], v34, s21, v[114:115]
	v_lshl_add_u64 v[18:19], v[18:19], 0, s[26:27]
	v_lshl_add_u64 v[18:19], v[18:19], 0, s[64:65]
	v_lshl_add_u64 v[18:19], v[18:19], 0, v[0:1]
	s_nop 1
	global_store_dwordx2 v[18:19], v[28:29], off offset:8
	s_nop 1
	v_add_u32_e32 v18, s19, v153
	s_nop 1
	s_nop 0
	s_nop 1
	s_nop 0
	s_nop 1
	s_nop 0
	s_nop 1
	s_nop 1
	s_nop 1
	s_nop 0
	s_nop 1
	s_nop 0
	s_nop 1
	s_nop 0
	s_nop 1
	s_nop 0
	s_nop 1
	s_nop 1
	v_mul_f32_e32 v12, 0xbfb8aa3b, v6
	v_exp_f32_e32 v12, v12
	s_nop 0
	v_add_f32_e32 v12, 1.0, v12
	v_rcp_f32_e32 v12, v12
	s_nop 0
	v_mul_f32_e32 v6, v6, v12
	v_mul_f32_e32 v2, v2, v6
	v_mul_f32_e32 v6, 0xbfb8aa3b, v7
	v_exp_f32_e32 v6, v6
	s_nop 0
	v_add_f32_e32 v6, 1.0, v6
	v_rcp_f32_e32 v6, v6
	s_nop 0
	v_mul_f32_e32 v6, v7, v6
	v_mul_f32_e32 v3, v3, v6
	v_cvt_pk_bf16_f32 v12, v2, v3
	v_mul_f32_e32 v2, 0xbfb8aa3b, v8
	v_mul_f32_e32 v3, 0xbfb8aa3b, v9
	v_exp_f32_e32 v2, v2
	v_exp_f32_e32 v3, v3
	v_add_f32_e32 v2, 1.0, v2
	v_add_f32_e32 v3, 1.0, v3
	v_rcp_f32_e32 v2, v2
	v_rcp_f32_e32 v3, v3
	v_mul_f32_e32 v2, v8, v2
	v_mul_f32_e32 v3, v9, v3
	v_mul_f32_e32 v2, v4, v2
	v_mul_f32_e32 v3, v5, v3
	v_cvt_pk_bf16_f32 v13, v2, v3
	v_mad_i64_i32 v[2:3], s[30:31], v18, s21, v[114:115]
	v_lshl_add_u64 v[2:3], v[2:3], 0, s[26:27]
	v_lshl_add_u64 v[2:3], v[2:3], 0, s[64:65]
	v_lshl_add_u64 v[2:3], v[2:3], 0, v[0:1]
	s_mov_b64 s[26:27], -1
	s_nop 1
	global_store_dwordx2 v[2:3], v[12:13], off offset:8
